# hand-written fix-up phase: batched carry loads + rolling 4-row prefetch window (was 16 dependent load-compute-store trips)
# speedup vs baseline: 1.0661x; 1.0017x over previous
; __device__ __forceinline__ int tid_() { int t = threadIdx.x; asm volatile("" : "+v"(t)); return t; }
; __device__ __forceinline__ int bid_() { int t = blockIdx.x; asm volatile("" : "+s"(t)); return t; }
; __device__ __forceinline__ int gdim_() { int t = gridDim.x; asm volatile("" : "+s"(t)); return t; }
; __device__ __forceinline__ void fixup_phase(KP p, int l) {
;     bf16_t* P = (bf16_t*)(p->ws + WS_BIG);
;     const bf16_t* HLOC = (const bf16_t*)(p->ws + WS_R2); const bf16_t* PCUM = (const bf16_t*)(p->ws + WS_R2 + R2_PCUM);
;     const float* SUMM = (const float*)(p->ws + WS_SUMM);
;     const int gt = bid_() * 512 + tid_(), NT = gdim_() * 512;
;     for (int it = gt; it < (M / 16) * 128; it += NT) {
;         const int tile = it >> 7, c0 = (it & 127) * 8, m0 = tile * 16;
;         float carry[8];
; #pragma unroll
;         for (int e = 0; e < 8; ++e) carry[e] = 0.f;
;         int b = 0, t0 = 1;
;         if (tile < 1032) {
;             b = tile / 129; const int tb = tile - b * 129; int q = tb >> 3; if (q > 15) q = 15; t0 = tb * 16;
;             for (int qq = 0; qq < q; ++qq) { float Pq[8], Hq[8]; const float* s = SUMM + (size_t)(b * 16 + qq) * 2 * D + c0; load8f(s, Pq); load8f(s + D, Hq);
; #pragma unroll
;                 for (int e = 0; e < 8; ++e) carry[e] = Pq[e] * carry[e] + Hq[e]; }
;         }
.LBB0_409:
	s_or_b64 exec, exec, s[4:5]
	s_mov_b64 s[6:7], s[94:95]
	s_mov_b32 s4, s2
	v_mov_b32_e32 v0, v209
	s_waitcnt lgkmcnt(0)
	s_barrier
	s_mov_b64 s[8:9], exec
	s_lshl_b32 s16, s3, 9
	s_lshl_b32 s18, s56, 3
	s_lshl_b32 s19, s3, 12
	s_load_dwordx2 s[34:35], s[6:7], 0xe8
	s_load_dwordx2 s[72:73], s[6:7], 0xe0
	v_readfirstlane_b32 s5, v0
	v_and_b32_e32 v2, 63, v0
	s_nop 2
	s_lshr_b32 s5, s5, 6
	s_lshl_b32 s5, s5, 6
	s_lshl_b32 s57, s4, 9
	s_add_i32 s57, s57, s5
	s_waitcnt lgkmcnt(0)
.Lfx_loop:
	s_cmp_lt_u32 s57, 0x20800
	s_cbranch_scc0 .Lfx_done
	s_lshr_b32 s21, s57, 7
	s_and_b32 s23, s57, 64
	v_or_b32_e32 v3, s23, v2
	v_lshlrev_b32_e32 v26, 4, v3
	v_lshlrev_b32_e32 v31, 5, v3
	v_mov_b32_e32 v27, v26
	s_lshl_b32 s48, s21, 4
	v_mov_b32_e32 v18, 0
	v_mov_b32_e32 v19, 0
	v_mov_b32_e32 v20, 0
	v_mov_b32_e32 v21, 0
	v_mov_b32_e32 v22, 0
	v_mov_b32_e32 v23, 0
	v_mov_b32_e32 v24, 0
	v_mov_b32_e32 v25, 0
	s_mov_b32 s43, 0
	s_cmp_lt_u32 s21, 0x408
	s_cbranch_scc0 .Lfx_nocarry
	s_mul_hi_u32 s10, s21, 0x1fc07f1
	s_mul_i32 s44, s10, 0x81
	s_sub_i32 s44, s21, s44
	s_cmp_eq_u32 s44, 0x80
	s_cselect_b32 s43, 1, 0
	s_lshr_b32 s11, s44, 3
	s_min_u32 s11, s11, 15
	s_cmp_eq_u32 s11, 0
	s_cbranch_scc1 .Lfx_nocarry
	s_lshl_b32 s44, s10, 17
	s_add_u32 s24, s34, 0x24c8000
	s_addc_u32 s25, s35, 0
	s_add_u32 s24, s24, s44
	s_addc_u32 s25, s25, 0
	global_load_dwordx4 v[32:35], v31, s[24:25]
	global_load_dwordx4 v[36:39], v31, s[24:25] offset:16
	s_add_u32 s98, s24, 0x1000
	s_addc_u32 s99, s25, 0
	global_load_dwordx4 v[40:43], v31, s[98:99]
	global_load_dwordx4 v[44:47], v31, s[98:99] offset:16
	s_add_u32 s24, s24, 0x2000
	s_addc_u32 s25, s25, 0
	s_cmp_le_u32 s11, 1
	s_cbranch_scc1 .Lfx_cw0
	global_load_dwordx4 v[48:51], v31, s[24:25]
	global_load_dwordx4 v[52:55], v31, s[24:25] offset:16
	s_add_u32 s98, s24, 0x1000
	s_addc_u32 s99, s25, 0
	global_load_dwordx4 v[56:59], v31, s[98:99]
	global_load_dwordx4 v[60:63], v31, s[98:99] offset:16
	s_add_u32 s24, s24, 0x2000
	s_addc_u32 s25, s25, 0
	s_cmp_le_u32 s11, 2
	s_cbranch_scc1 .Lfx_cw0
	global_load_dwordx4 v[64:67], v31, s[24:25]
	global_load_dwordx4 v[68:71], v31, s[24:25] offset:16
	s_add_u32 s98, s24, 0x1000
	s_addc_u32 s99, s25, 0
	global_load_dwordx4 v[72:75], v31, s[98:99]
	global_load_dwordx4 v[76:79], v31, s[98:99] offset:16
	s_add_u32 s24, s24, 0x2000
	s_addc_u32 s25, s25, 0
	s_cmp_le_u32 s11, 3
	s_cbranch_scc1 .Lfx_cw0
	global_load_dwordx4 v[80:83], v31, s[24:25]
	global_load_dwordx4 v[84:87], v31, s[24:25] offset:16
	s_add_u32 s98, s24, 0x1000
	s_addc_u32 s99, s25, 0
	global_load_dwordx4 v[88:91], v31, s[98:99]
	global_load_dwordx4 v[92:95], v31, s[98:99] offset:16
	s_add_u32 s24, s24, 0x2000
	s_addc_u32 s25, s25, 0
	s_cmp_le_u32 s11, 4
	s_cbranch_scc1 .Lfx_cw0
	global_load_dwordx4 v[96:99], v31, s[24:25]
	global_load_dwordx4 v[100:103], v31, s[24:25] offset:16
	s_add_u32 s98, s24, 0x1000
	s_addc_u32 s99, s25, 0
	global_load_dwordx4 v[104:107], v31, s[98:99]
	global_load_dwordx4 v[108:111], v31, s[98:99] offset:16
	s_add_u32 s24, s24, 0x2000
	s_addc_u32 s25, s25, 0
	s_cmp_le_u32 s11, 5
	s_cbranch_scc1 .Lfx_cw0
	global_load_dwordx4 v[112:115], v31, s[24:25]
	global_load_dwordx4 v[116:119], v31, s[24:25] offset:16
	s_add_u32 s98, s24, 0x1000
	s_addc_u32 s99, s25, 0
	global_load_dwordx4 v[120:123], v31, s[98:99]
	global_load_dwordx4 v[124:127], v31, s[98:99] offset:16
	s_add_u32 s24, s24, 0x2000
	s_addc_u32 s25, s25, 0
	s_cmp_le_u32 s11, 6
	s_cbranch_scc1 .Lfx_cw0
	global_load_dwordx4 v[128:131], v31, s[24:25]
	global_load_dwordx4 v[132:135], v31, s[24:25] offset:16
	s_add_u32 s98, s24, 0x1000
	s_addc_u32 s99, s25, 0
	global_load_dwordx4 v[136:139], v31, s[98:99]
	global_load_dwordx4 v[140:143], v31, s[98:99] offset:16
	s_add_u32 s24, s24, 0x2000
	s_addc_u32 s25, s25, 0
	s_cmp_le_u32 s11, 7
	s_cbranch_scc1 .Lfx_cw0
	global_load_dwordx4 v[144:147], v31, s[24:25]
	global_load_dwordx4 v[148:151], v31, s[24:25] offset:16
	s_add_u32 s98, s24, 0x1000
	s_addc_u32 s99, s25, 0
	global_load_dwordx4 v[152:155], v31, s[98:99]
	global_load_dwordx4 v[156:159], v31, s[98:99] offset:16
	s_add_u32 s24, s24, 0x2000
	s_addc_u32 s25, s25, 0
.Lfx_cw0:
	s_waitcnt vmcnt(0)
	v_fma_f32 v18, v32, v18, v40
	v_fma_f32 v19, v33, v19, v41
	v_fma_f32 v20, v34, v20, v42
	v_fma_f32 v21, v35, v21, v43
	v_fma_f32 v22, v36, v22, v44
	v_fma_f32 v23, v37, v23, v45
	v_fma_f32 v24, v38, v24, v46
	v_fma_f32 v25, v39, v25, v47
	s_cmp_le_u32 s11, 1
	s_cbranch_scc1 .Lfx_nocarry
	v_fma_f32 v18, v48, v18, v56
	v_fma_f32 v19, v49, v19, v57
	v_fma_f32 v20, v50, v20, v58
	v_fma_f32 v21, v51, v21, v59
	v_fma_f32 v22, v52, v22, v60
	v_fma_f32 v23, v53, v23, v61
	v_fma_f32 v24, v54, v24, v62
	v_fma_f32 v25, v55, v25, v63
	s_cmp_le_u32 s11, 2
	s_cbranch_scc1 .Lfx_nocarry
	v_fma_f32 v18, v64, v18, v72
	v_fma_f32 v19, v65, v19, v73
	v_fma_f32 v20, v66, v20, v74
	v_fma_f32 v21, v67, v21, v75
	v_fma_f32 v22, v68, v22, v76
	v_fma_f32 v23, v69, v23, v77
	v_fma_f32 v24, v70, v24, v78
	v_fma_f32 v25, v71, v25, v79
	s_cmp_le_u32 s11, 3
	s_cbranch_scc1 .Lfx_nocarry
	v_fma_f32 v18, v80, v18, v88
	v_fma_f32 v19, v81, v19, v89
	v_fma_f32 v20, v82, v20, v90
	v_fma_f32 v21, v83, v21, v91
	v_fma_f32 v22, v84, v22, v92
	v_fma_f32 v23, v85, v23, v93
	v_fma_f32 v24, v86, v24, v94
	v_fma_f32 v25, v87, v25, v95
	s_cmp_le_u32 s11, 4
	s_cbranch_scc1 .Lfx_nocarry
	v_fma_f32 v18, v96, v18, v104
	v_fma_f32 v19, v97, v19, v105
	v_fma_f32 v20, v98, v20, v106
	v_fma_f32 v21, v99, v21, v107
	v_fma_f32 v22, v100, v22, v108
	v_fma_f32 v23, v101, v23, v109
	v_fma_f32 v24, v102, v24, v110
	v_fma_f32 v25, v103, v25, v111
	s_cmp_le_u32 s11, 5
	s_cbranch_scc1 .Lfx_nocarry
; __device__ __forceinline__ void fixup_phase(KP p, int l) {
;     ...
;             for (int qq = 0; qq < q; ++qq) { float Pq[8], Hq[8]; const float* s = SUMM + (size_t)(b * 16 + qq) * 2 * D + c0; load8f(s, Pq); load8f(s + D, Hq);
; #pragma unroll
;                 for (int e = 0; e < 8; ++e) carry[e] = Pq[e] * carry[e] + Hq[e]; }
	v_fma_f32 v18, v112, v18, v120
	v_fma_f32 v19, v113, v19, v121
	v_fma_f32 v20, v114, v20, v122
	v_fma_f32 v21, v115, v21, v123
	v_fma_f32 v22, v116, v22, v124
	v_fma_f32 v23, v117, v23, v125
	v_fma_f32 v24, v118, v24, v126
	v_fma_f32 v25, v119, v25, v127
	s_cmp_le_u32 s11, 6
	s_cbranch_scc1 .Lfx_nocarry
	v_fma_f32 v18, v128, v18, v136
	v_fma_f32 v19, v129, v19, v137
	v_fma_f32 v20, v130, v20, v138
	v_fma_f32 v21, v131, v21, v139
	v_fma_f32 v22, v132, v22, v140
	v_fma_f32 v23, v133, v23, v141
	v_fma_f32 v24, v134, v24, v142
	v_fma_f32 v25, v135, v25, v143
	s_cmp_le_u32 s11, 7
	s_cbranch_scc1 .Lfx_nocarry
	v_fma_f32 v18, v144, v18, v152
	v_fma_f32 v19, v145, v19, v153
	v_fma_f32 v20, v146, v20, v154
	v_fma_f32 v21, v147, v21, v155
	v_fma_f32 v22, v148, v22, v156
	v_fma_f32 v23, v149, v23, v157
	v_fma_f32 v24, v150, v24, v158
	v_fma_f32 v25, v151, v25, v159
	s_cmp_le_u32 s11, 8
	s_cbranch_scc1 .Lfx_cw1
	global_load_dwordx4 v[32:35], v31, s[24:25]
	global_load_dwordx4 v[36:39], v31, s[24:25] offset:16
	s_add_u32 s98, s24, 0x1000
	s_addc_u32 s99, s25, 0
	global_load_dwordx4 v[40:43], v31, s[98:99]
	global_load_dwordx4 v[44:47], v31, s[98:99] offset:16
	s_add_u32 s24, s24, 0x2000
	s_addc_u32 s25, s25, 0
	s_cmp_le_u32 s11, 9
	s_cbranch_scc1 .Lfx_cw1
	global_load_dwordx4 v[48:51], v31, s[24:25]
	global_load_dwordx4 v[52:55], v31, s[24:25] offset:16
	s_add_u32 s98, s24, 0x1000
	s_addc_u32 s99, s25, 0
	global_load_dwordx4 v[56:59], v31, s[98:99]
	global_load_dwordx4 v[60:63], v31, s[98:99] offset:16
	s_add_u32 s24, s24, 0x2000
	s_addc_u32 s25, s25, 0
	s_cmp_le_u32 s11, 10
	s_cbranch_scc1 .Lfx_cw1
	global_load_dwordx4 v[64:67], v31, s[24:25]
	global_load_dwordx4 v[68:71], v31, s[24:25] offset:16
	s_add_u32 s98, s24, 0x1000
	s_addc_u32 s99, s25, 0
	global_load_dwordx4 v[72:75], v31, s[98:99]
	global_load_dwordx4 v[76:79], v31, s[98:99] offset:16
	s_add_u32 s24, s24, 0x2000
	s_addc_u32 s25, s25, 0
	s_cmp_le_u32 s11, 11
	s_cbranch_scc1 .Lfx_cw1
	global_load_dwordx4 v[80:83], v31, s[24:25]
	global_load_dwordx4 v[84:87], v31, s[24:25] offset:16
	s_add_u32 s98, s24, 0x1000
	s_addc_u32 s99, s25, 0
	global_load_dwordx4 v[88:91], v31, s[98:99]
	global_load_dwordx4 v[92:95], v31, s[98:99] offset:16
	s_add_u32 s24, s24, 0x2000
	s_addc_u32 s25, s25, 0
	s_cmp_le_u32 s11, 12
	s_cbranch_scc1 .Lfx_cw1
	global_load_dwordx4 v[96:99], v31, s[24:25]
	global_load_dwordx4 v[100:103], v31, s[24:25] offset:16
	s_add_u32 s98, s24, 0x1000
	s_addc_u32 s99, s25, 0
	global_load_dwordx4 v[104:107], v31, s[98:99]
	global_load_dwordx4 v[108:111], v31, s[98:99] offset:16
	s_add_u32 s24, s24, 0x2000
	s_addc_u32 s25, s25, 0
	s_cmp_le_u32 s11, 13
	s_cbranch_scc1 .Lfx_cw1
	global_load_dwordx4 v[112:115], v31, s[24:25]
	global_load_dwordx4 v[116:119], v31, s[24:25] offset:16
	s_add_u32 s98, s24, 0x1000
	s_addc_u32 s99, s25, 0
	global_load_dwordx4 v[120:123], v31, s[98:99]
	global_load_dwordx4 v[124:127], v31, s[98:99] offset:16
	s_add_u32 s24, s24, 0x2000
	s_addc_u32 s25, s25, 0
	s_cmp_le_u32 s11, 14
	s_cbranch_scc1 .Lfx_cw1
	global_load_dwordx4 v[128:131], v31, s[24:25]
	global_load_dwordx4 v[132:135], v31, s[24:25] offset:16
	s_add_u32 s98, s24, 0x1000
	s_addc_u32 s99, s25, 0
	global_load_dwordx4 v[136:139], v31, s[98:99]
	global_load_dwordx4 v[140:143], v31, s[98:99] offset:16
	s_add_u32 s24, s24, 0x2000
	s_addc_u32 s25, s25, 0
	s_cmp_le_u32 s11, 15
	s_cbranch_scc1 .Lfx_cw1
	global_load_dwordx4 v[144:147], v31, s[24:25]
	global_load_dwordx4 v[148:151], v31, s[24:25] offset:16
	s_add_u32 s98, s24, 0x1000
	s_addc_u32 s99, s25, 0
	global_load_dwordx4 v[152:155], v31, s[98:99]
	global_load_dwordx4 v[156:159], v31, s[98:99] offset:16
	s_add_u32 s24, s24, 0x2000
	s_addc_u32 s25, s25, 0
.Lfx_cw1:
	s_waitcnt vmcnt(0)
	s_cmp_le_u32 s11, 8
	s_cbranch_scc1 .Lfx_nocarry
	v_fma_f32 v18, v32, v18, v40
	v_fma_f32 v19, v33, v19, v41
	v_fma_f32 v20, v34, v20, v42
	v_fma_f32 v21, v35, v21, v43
	v_fma_f32 v22, v36, v22, v44
	v_fma_f32 v23, v37, v23, v45
	v_fma_f32 v24, v38, v24, v46
	v_fma_f32 v25, v39, v25, v47
	s_cmp_le_u32 s11, 9
	s_cbranch_scc1 .Lfx_nocarry
	v_fma_f32 v18, v48, v18, v56
	v_fma_f32 v19, v49, v19, v57
	v_fma_f32 v20, v50, v20, v58
	v_fma_f32 v21, v51, v21, v59
	v_fma_f32 v22, v52, v22, v60
	v_fma_f32 v23, v53, v23, v61
	v_fma_f32 v24, v54, v24, v62
	v_fma_f32 v25, v55, v25, v63
	s_cmp_le_u32 s11, 10
	s_cbranch_scc1 .Lfx_nocarry
	v_fma_f32 v18, v64, v18, v72
	v_fma_f32 v19, v65, v19, v73
	v_fma_f32 v20, v66, v20, v74
	v_fma_f32 v21, v67, v21, v75
	v_fma_f32 v22, v68, v22, v76
	v_fma_f32 v23, v69, v23, v77
	v_fma_f32 v24, v70, v24, v78
	v_fma_f32 v25, v71, v25, v79
	s_cmp_le_u32 s11, 11
	s_cbranch_scc1 .Lfx_nocarry
	v_fma_f32 v18, v80, v18, v88
	v_fma_f32 v19, v81, v19, v89
	v_fma_f32 v20, v82, v20, v90
	v_fma_f32 v21, v83, v21, v91
	v_fma_f32 v22, v84, v22, v92
	v_fma_f32 v23, v85, v23, v93
	v_fma_f32 v24, v86, v24, v94
	v_fma_f32 v25, v87, v25, v95
	s_cmp_le_u32 s11, 12
	s_cbranch_scc1 .Lfx_nocarry
	v_fma_f32 v18, v96, v18, v104
	v_fma_f32 v19, v97, v19, v105
	v_fma_f32 v20, v98, v20, v106
	v_fma_f32 v21, v99, v21, v107
	v_fma_f32 v22, v100, v22, v108
	v_fma_f32 v23, v101, v23, v109
	v_fma_f32 v24, v102, v24, v110
	v_fma_f32 v25, v103, v25, v111
	s_cmp_le_u32 s11, 13
	s_cbranch_scc1 .Lfx_nocarry
	v_fma_f32 v18, v112, v18, v120
	v_fma_f32 v19, v113, v19, v121
	v_fma_f32 v20, v114, v20, v122
	v_fma_f32 v21, v115, v21, v123
	v_fma_f32 v22, v116, v22, v124
	v_fma_f32 v23, v117, v23, v125
	v_fma_f32 v24, v118, v24, v126
	v_fma_f32 v25, v119, v25, v127
	s_cmp_le_u32 s11, 14
	s_cbranch_scc1 .Lfx_nocarry
	v_fma_f32 v18, v128, v18, v136
	v_fma_f32 v19, v129, v19, v137
	v_fma_f32 v20, v130, v20, v138
	v_fma_f32 v21, v131, v21, v139
	v_fma_f32 v22, v132, v22, v140
	v_fma_f32 v23, v133, v23, v141
	v_fma_f32 v24, v134, v24, v142
	v_fma_f32 v25, v135, v25, v143
	s_cmp_le_u32 s11, 15
	s_cbranch_scc1 .Lfx_nocarry
	v_fma_f32 v18, v144, v18, v152
	v_fma_f32 v19, v145, v19, v153
	v_fma_f32 v20, v146, v20, v154
	v_fma_f32 v21, v147, v21, v155
	v_fma_f32 v22, v148, v22, v156
	v_fma_f32 v23, v149, v23, v157
	v_fma_f32 v24, v150, v24, v158
	v_fma_f32 v25, v151, v25, v159
; __device__ __forceinline__ u32x4 pack8(const float (&f)[8]) { u32x4 o; o.x = cvt_pk_bf16(f[0], f[1]); o.y = cvt_pk_bf16(f[2], f[3]); o.z = cvt_pk_bf16(f[4], f[5]); o.w = cvt_pk_bf16(f[6], f[7]); return o; }
; __device__ __forceinline__ float sigmoidf_(float x) { return __builtin_amdgcn_rcpf(1.0f + __expf(-x)); }
; __device__ __forceinline__ float gelu_tanh(float x) { return x * sigmoidf_(1.5957691216057308f * (x + 0.044715f * x * x * x)); }
; __device__ __forceinline__ void fixup_phase(KP p, int l) {
;     ...
; #pragma unroll 4
;         for (int i = 0; i < 16; ++i) {
;             const size_t m = (size_t)(m0 + i);
;             float hl[8], pc[8], gr[8], o[8], h[8];
;             unpack8(__builtin_nontemporal_load((const u32x4*)(HLOC + m * D + c0)), hl); unpack8(__builtin_nontemporal_load((const u32x4*)(PCUM + m * D + c0)), pc);
;             bf16_t* gp = P + m * DP + C_GR + c0; unpack8(*(const u32x4*)gp, gr);
; #pragma unroll
;             for (int e = 0; e < 8; ++e) { h[e] = hl[e] + pc[e] * carry[e]; o[e] = gelu_tanh(gr[e]) * h[e]; }
;             *(u32x4*)gp = pack8(o);
.Lfx_nocarry:
	s_lshl_b32 s44, s48, 11
	s_add_u32 s12, s34, 0x14a48000
	s_addc_u32 s13, s35, 0
	s_add_u32 s12, s12, s44
	s_addc_u32 s13, s13, 0
	s_add_u32 s14, s12, 0x2080000
	s_addc_u32 s15, s13, 0
	s_mul_i32 s44, s48, 0x2800
	s_add_u32 s96, s34, 0x66c9800
	s_addc_u32 s97, s35, 0
	s_add_u32 s96, s96, s44
	s_addc_u32 s97, s97, 0
	s_mov_b32 s24, s96
	s_mov_b32 s25, s97
	global_load_dwordx4 v[32:35], v26, s[12:13] nt
	global_load_dwordx4 v[36:39], v26, s[14:15] nt
	global_load_dwordx4 v[40:43], v26, s[96:97]
	s_add_u32 s12, s12, 0x800
	s_addc_u32 s13, s13, 0
	s_add_u32 s14, s14, 0x800
	s_addc_u32 s15, s15, 0
	s_add_u32 s96, s96, 0x2800
	s_addc_u32 s97, s97, 0
	global_load_dwordx4 v[44:47], v26, s[12:13] nt
	global_load_dwordx4 v[48:51], v26, s[14:15] nt
	global_load_dwordx4 v[52:55], v26, s[96:97]
	s_add_u32 s12, s12, 0x800
	s_addc_u32 s13, s13, 0
	s_add_u32 s14, s14, 0x800
	s_addc_u32 s15, s15, 0
	s_add_u32 s96, s96, 0x2800
	s_addc_u32 s97, s97, 0
	global_load_dwordx4 v[56:59], v26, s[12:13] nt
	global_load_dwordx4 v[60:63], v26, s[14:15] nt
	global_load_dwordx4 v[64:67], v26, s[96:97]
	s_add_u32 s12, s12, 0x800
	s_addc_u32 s13, s13, 0
	s_add_u32 s14, s14, 0x800
	s_addc_u32 s15, s15, 0
	s_add_u32 s96, s96, 0x2800
	s_addc_u32 s97, s97, 0
	global_load_dwordx4 v[68:71], v26, s[12:13] nt
	global_load_dwordx4 v[72:75], v26, s[14:15] nt
	global_load_dwordx4 v[76:79], v26, s[96:97]
	s_add_u32 s12, s12, 0x800
	s_addc_u32 s13, s13, 0
	s_add_u32 s14, s14, 0x800
	s_addc_u32 s15, s15, 0
	s_add_u32 s96, s96, 0x2800
	s_addc_u32 s97, s97, 0
	s_waitcnt vmcnt(9)
	v_lshlrev_b32_e32 v80, 16, v32
	v_and_b32_e32 v81, 0xffff0000, v32
	v_lshlrev_b32_e32 v82, 16, v33
	v_and_b32_e32 v83, 0xffff0000, v33
	v_lshlrev_b32_e32 v84, 16, v34
	v_and_b32_e32 v85, 0xffff0000, v34
	v_lshlrev_b32_e32 v86, 16, v35
	v_and_b32_e32 v87, 0xffff0000, v35
	v_lshlrev_b32_e32 v96, 16, v36
	v_and_b32_e32 v97, 0xffff0000, v36
	v_lshlrev_b32_e32 v98, 16, v37
	v_and_b32_e32 v99, 0xffff0000, v37
	v_lshlrev_b32_e32 v100, 16, v38
	v_and_b32_e32 v101, 0xffff0000, v38
	v_lshlrev_b32_e32 v102, 16, v39
	v_and_b32_e32 v103, 0xffff0000, v39
	v_lshlrev_b32_e32 v88, 16, v40
	v_and_b32_e32 v89, 0xffff0000, v40
	v_lshlrev_b32_e32 v90, 16, v41
	v_and_b32_e32 v91, 0xffff0000, v41
	v_lshlrev_b32_e32 v92, 16, v42
	v_and_b32_e32 v93, 0xffff0000, v42
	v_lshlrev_b32_e32 v94, 16, v43
	v_and_b32_e32 v95, 0xffff0000, v43
	v_fmac_f32_e32 v80, v96, v18
	v_fmac_f32_e32 v81, v97, v19
	v_fmac_f32_e32 v82, v98, v20
	v_fmac_f32_e32 v83, v99, v21
	v_fmac_f32_e32 v84, v100, v22
	v_fmac_f32_e32 v85, v101, v23
	v_fmac_f32_e32 v86, v102, v24
	v_fmac_f32_e32 v87, v103, v25
	v_mul_f32_e32 v104, 0x3d372713, v88
	v_mul_f32_e32 v105, 0x3d372713, v89
	v_mul_f32_e32 v106, 0x3d372713, v90
	v_mul_f32_e32 v107, 0x3d372713, v91
	v_mul_f32_e32 v108, 0x3d372713, v92
	v_mul_f32_e32 v109, 0x3d372713, v93
	v_mul_f32_e32 v110, 0x3d372713, v94
	v_mul_f32_e32 v111, 0x3d372713, v95
	v_mul_f32_e32 v104, v104, v88
	v_mul_f32_e32 v105, v105, v89
	v_mul_f32_e32 v106, v106, v90
	v_mul_f32_e32 v107, v107, v91
	v_mul_f32_e32 v108, v108, v92
	v_mul_f32_e32 v109, v109, v93
	v_mul_f32_e32 v110, v110, v94
	v_mul_f32_e32 v111, v111, v95
	v_fma_f32 v104, v104, v88, v88
	v_fma_f32 v105, v105, v89, v89
	v_fma_f32 v106, v106, v90, v90
	v_fma_f32 v107, v107, v91, v91
	v_fma_f32 v108, v108, v92, v92
	v_fma_f32 v109, v109, v93, v93
	v_fma_f32 v110, v110, v94, v94
	v_fma_f32 v111, v111, v95, v95
	v_mul_f32_e32 v104, 0x3fcc422a, v104
	v_mul_f32_e32 v105, 0x3fcc422a, v105
	v_mul_f32_e32 v106, 0x3fcc422a, v106
	v_mul_f32_e32 v107, 0x3fcc422a, v107
	v_mul_f32_e32 v108, 0x3fcc422a, v108
	v_mul_f32_e32 v109, 0x3fcc422a, v109
	v_mul_f32_e32 v110, 0x3fcc422a, v110
	v_mul_f32_e32 v111, 0x3fcc422a, v111
	v_mul_f32_e32 v104, 0xbfb8aa3b, v104
	v_mul_f32_e32 v105, 0xbfb8aa3b, v105
	v_mul_f32_e32 v106, 0xbfb8aa3b, v106
	v_mul_f32_e32 v107, 0xbfb8aa3b, v107
	v_mul_f32_e32 v108, 0xbfb8aa3b, v108
	v_mul_f32_e32 v109, 0xbfb8aa3b, v109
	v_mul_f32_e32 v110, 0xbfb8aa3b, v110
	v_mul_f32_e32 v111, 0xbfb8aa3b, v111
	v_exp_f32_e32 v104, v104
	v_exp_f32_e32 v105, v105
	v_exp_f32_e32 v106, v106
	v_exp_f32_e32 v107, v107
	v_exp_f32_e32 v108, v108
	v_exp_f32_e32 v109, v109
	v_exp_f32_e32 v110, v110
	v_exp_f32_e32 v111, v111
	v_add_f32_e32 v104, 1.0, v104
	v_add_f32_e32 v105, 1.0, v105
	v_add_f32_e32 v106, 1.0, v106
	v_add_f32_e32 v107, 1.0, v107
	v_add_f32_e32 v108, 1.0, v108
	v_add_f32_e32 v109, 1.0, v109
	v_add_f32_e32 v110, 1.0, v110
	v_add_f32_e32 v111, 1.0, v111
	v_rcp_f32_e32 v104, v104
	v_rcp_f32_e32 v105, v105
	v_rcp_f32_e32 v106, v106
	v_rcp_f32_e32 v107, v107
	v_rcp_f32_e32 v108, v108
	v_rcp_f32_e32 v109, v109
	v_rcp_f32_e32 v110, v110
	v_rcp_f32_e32 v111, v111
	v_mul_f32_e32 v104, v104, v88
	v_mul_f32_e32 v105, v105, v89
	v_mul_f32_e32 v106, v106, v90
	v_mul_f32_e32 v107, v107, v91
	v_mul_f32_e32 v108, v108, v92
	v_mul_f32_e32 v109, v109, v93
	v_mul_f32_e32 v110, v110, v94
	v_mul_f32_e32 v111, v111, v95
	v_mul_f32_e32 v104, v80, v104
	v_mul_f32_e32 v105, v81, v105
	v_mul_f32_e32 v106, v82, v106
	v_mul_f32_e32 v107, v83, v107
	v_mul_f32_e32 v108, v84, v108
	v_mul_f32_e32 v109, v85, v109
	v_mul_f32_e32 v110, v86, v110
	v_mul_f32_e32 v111, v87, v111
	v_cvt_pk_bf16_f32 v112, v104, v105
	v_cvt_pk_bf16_f32 v113, v106, v107
	v_cvt_pk_bf16_f32 v114, v108, v109
	v_cvt_pk_bf16_f32 v115, v110, v111
	global_store_dwordx4 v27, v[112:115], s[24:25]
	s_add_u32 s24, s24, 0x2800
	s_addc_u32 s25, s25, 0
	global_load_dwordx4 v[32:35], v26, s[12:13] nt
	global_load_dwordx4 v[36:39], v26, s[14:15] nt
	global_load_dwordx4 v[40:43], v26, s[96:97]
	s_add_u32 s12, s12, 0x800
	s_addc_u32 s13, s13, 0
	s_add_u32 s14, s14, 0x800
	s_addc_u32 s15, s15, 0
	s_add_u32 s96, s96, 0x2800
	s_addc_u32 s97, s97, 0
	s_waitcnt vmcnt(10)
; __device__ __forceinline__ u32x4 pack8(const float (&f)[8]) { u32x4 o; o.x = cvt_pk_bf16(f[0], f[1]); o.y = cvt_pk_bf16(f[2], f[3]); o.z = cvt_pk_bf16(f[4], f[5]); o.w = cvt_pk_bf16(f[6], f[7]); return o; }
; __device__ __forceinline__ float sigmoidf_(float x) { return __builtin_amdgcn_rcpf(1.0f + __expf(-x)); }
; __device__ __forceinline__ float gelu_tanh(float x) { return x * sigmoidf_(1.5957691216057308f * (x + 0.044715f * x * x * x)); }
; __device__ __forceinline__ void fixup_phase(KP p, int l) {
;     ...
; #pragma unroll 4
;         for (int i = 0; i < 16; ++i) {
;             const size_t m = (size_t)(m0 + i);
;             float hl[8], pc[8], gr[8], o[8], h[8];
;             unpack8(__builtin_nontemporal_load((const u32x4*)(HLOC + m * D + c0)), hl); unpack8(__builtin_nontemporal_load((const u32x4*)(PCUM + m * D + c0)), pc);
;             bf16_t* gp = P + m * DP + C_GR + c0; unpack8(*(const u32x4*)gp, gr);
; #pragma unroll
;             for (int e = 0; e < 8; ++e) { h[e] = hl[e] + pc[e] * carry[e]; o[e] = gelu_tanh(gr[e]) * h[e]; }
;             *(u32x4*)gp = pack8(o);
	v_lshlrev_b32_e32 v80, 16, v44
	v_and_b32_e32 v81, 0xffff0000, v44
	v_lshlrev_b32_e32 v82, 16, v45
	v_and_b32_e32 v83, 0xffff0000, v45
	v_lshlrev_b32_e32 v84, 16, v46
	v_and_b32_e32 v85, 0xffff0000, v46
	v_lshlrev_b32_e32 v86, 16, v47
	v_and_b32_e32 v87, 0xffff0000, v47
	v_lshlrev_b32_e32 v96, 16, v48
	v_and_b32_e32 v97, 0xffff0000, v48
	v_lshlrev_b32_e32 v98, 16, v49
	v_and_b32_e32 v99, 0xffff0000, v49
	v_lshlrev_b32_e32 v100, 16, v50
	v_and_b32_e32 v101, 0xffff0000, v50
	v_lshlrev_b32_e32 v102, 16, v51
	v_and_b32_e32 v103, 0xffff0000, v51
	v_lshlrev_b32_e32 v88, 16, v52
	v_and_b32_e32 v89, 0xffff0000, v52
	v_lshlrev_b32_e32 v90, 16, v53
	v_and_b32_e32 v91, 0xffff0000, v53
	v_lshlrev_b32_e32 v92, 16, v54
	v_and_b32_e32 v93, 0xffff0000, v54
	v_lshlrev_b32_e32 v94, 16, v55
	v_and_b32_e32 v95, 0xffff0000, v55
	v_fmac_f32_e32 v80, v96, v18
	v_fmac_f32_e32 v81, v97, v19
	v_fmac_f32_e32 v82, v98, v20
	v_fmac_f32_e32 v83, v99, v21
	v_fmac_f32_e32 v84, v100, v22
	v_fmac_f32_e32 v85, v101, v23
	v_fmac_f32_e32 v86, v102, v24
	v_fmac_f32_e32 v87, v103, v25
	v_mul_f32_e32 v104, 0x3d372713, v88
	v_mul_f32_e32 v105, 0x3d372713, v89
	v_mul_f32_e32 v106, 0x3d372713, v90
	v_mul_f32_e32 v107, 0x3d372713, v91
	v_mul_f32_e32 v108, 0x3d372713, v92
	v_mul_f32_e32 v109, 0x3d372713, v93
	v_mul_f32_e32 v110, 0x3d372713, v94
	v_mul_f32_e32 v111, 0x3d372713, v95
	v_mul_f32_e32 v104, v104, v88
	v_mul_f32_e32 v105, v105, v89
	v_mul_f32_e32 v106, v106, v90
	v_mul_f32_e32 v107, v107, v91
	v_mul_f32_e32 v108, v108, v92
	v_mul_f32_e32 v109, v109, v93
	v_mul_f32_e32 v110, v110, v94
	v_mul_f32_e32 v111, v111, v95
	v_fma_f32 v104, v104, v88, v88
	v_fma_f32 v105, v105, v89, v89
	v_fma_f32 v106, v106, v90, v90
	v_fma_f32 v107, v107, v91, v91
	v_fma_f32 v108, v108, v92, v92
	v_fma_f32 v109, v109, v93, v93
	v_fma_f32 v110, v110, v94, v94
	v_fma_f32 v111, v111, v95, v95
	v_mul_f32_e32 v104, 0x3fcc422a, v104
	v_mul_f32_e32 v105, 0x3fcc422a, v105
	v_mul_f32_e32 v106, 0x3fcc422a, v106
	v_mul_f32_e32 v107, 0x3fcc422a, v107
	v_mul_f32_e32 v108, 0x3fcc422a, v108
	v_mul_f32_e32 v109, 0x3fcc422a, v109
	v_mul_f32_e32 v110, 0x3fcc422a, v110
	v_mul_f32_e32 v111, 0x3fcc422a, v111
	v_mul_f32_e32 v104, 0xbfb8aa3b, v104
	v_mul_f32_e32 v105, 0xbfb8aa3b, v105
	v_mul_f32_e32 v106, 0xbfb8aa3b, v106
	v_mul_f32_e32 v107, 0xbfb8aa3b, v107
	v_mul_f32_e32 v108, 0xbfb8aa3b, v108
	v_mul_f32_e32 v109, 0xbfb8aa3b, v109
	v_mul_f32_e32 v110, 0xbfb8aa3b, v110
	v_mul_f32_e32 v111, 0xbfb8aa3b, v111
	v_exp_f32_e32 v104, v104
	v_exp_f32_e32 v105, v105
	v_exp_f32_e32 v106, v106
	v_exp_f32_e32 v107, v107
	v_exp_f32_e32 v108, v108
	v_exp_f32_e32 v109, v109
	v_exp_f32_e32 v110, v110
	v_exp_f32_e32 v111, v111
	v_add_f32_e32 v104, 1.0, v104
	v_add_f32_e32 v105, 1.0, v105
	v_add_f32_e32 v106, 1.0, v106
	v_add_f32_e32 v107, 1.0, v107
	v_add_f32_e32 v108, 1.0, v108
	v_add_f32_e32 v109, 1.0, v109
	v_add_f32_e32 v110, 1.0, v110
	v_add_f32_e32 v111, 1.0, v111
	v_rcp_f32_e32 v104, v104
	v_rcp_f32_e32 v105, v105
	v_rcp_f32_e32 v106, v106
	v_rcp_f32_e32 v107, v107
	v_rcp_f32_e32 v108, v108
	v_rcp_f32_e32 v109, v109
	v_rcp_f32_e32 v110, v110
	v_rcp_f32_e32 v111, v111
	v_mul_f32_e32 v104, v104, v88
	v_mul_f32_e32 v105, v105, v89
	v_mul_f32_e32 v106, v106, v90
	v_mul_f32_e32 v107, v107, v91
	v_mul_f32_e32 v108, v108, v92
	v_mul_f32_e32 v109, v109, v93
	v_mul_f32_e32 v110, v110, v94
	v_mul_f32_e32 v111, v111, v95
	v_mul_f32_e32 v104, v80, v104
	v_mul_f32_e32 v105, v81, v105
	v_mul_f32_e32 v106, v82, v106
	v_mul_f32_e32 v107, v83, v107
	v_mul_f32_e32 v108, v84, v108
	v_mul_f32_e32 v109, v85, v109
	v_mul_f32_e32 v110, v86, v110
	v_mul_f32_e32 v111, v87, v111
	v_cvt_pk_bf16_f32 v112, v104, v105
	v_cvt_pk_bf16_f32 v113, v106, v107
	v_cvt_pk_bf16_f32 v114, v108, v109
	v_cvt_pk_bf16_f32 v115, v110, v111
	global_store_dwordx4 v27, v[112:115], s[24:25]
	s_add_u32 s24, s24, 0x2800
	s_addc_u32 s25, s25, 0
	global_load_dwordx4 v[44:47], v26, s[12:13] nt
	global_load_dwordx4 v[48:51], v26, s[14:15] nt
	global_load_dwordx4 v[52:55], v26, s[96:97]
	s_add_u32 s12, s12, 0x800
	s_addc_u32 s13, s13, 0
	s_add_u32 s14, s14, 0x800
	s_addc_u32 s15, s15, 0
	s_add_u32 s96, s96, 0x2800
	s_addc_u32 s97, s97, 0
	s_waitcnt vmcnt(11)
	v_lshlrev_b32_e32 v80, 16, v56
	v_and_b32_e32 v81, 0xffff0000, v56
	v_lshlrev_b32_e32 v82, 16, v57
	v_and_b32_e32 v83, 0xffff0000, v57
	v_lshlrev_b32_e32 v84, 16, v58
	v_and_b32_e32 v85, 0xffff0000, v58
	v_lshlrev_b32_e32 v86, 16, v59
	v_and_b32_e32 v87, 0xffff0000, v59
	v_lshlrev_b32_e32 v96, 16, v60
	v_and_b32_e32 v97, 0xffff0000, v60
	v_lshlrev_b32_e32 v98, 16, v61
	v_and_b32_e32 v99, 0xffff0000, v61
	v_lshlrev_b32_e32 v100, 16, v62
	v_and_b32_e32 v101, 0xffff0000, v62
	v_lshlrev_b32_e32 v102, 16, v63
	v_and_b32_e32 v103, 0xffff0000, v63
	v_lshlrev_b32_e32 v88, 16, v64
	v_and_b32_e32 v89, 0xffff0000, v64
	v_lshlrev_b32_e32 v90, 16, v65
	v_and_b32_e32 v91, 0xffff0000, v65
	v_lshlrev_b32_e32 v92, 16, v66
	v_and_b32_e32 v93, 0xffff0000, v66
	v_lshlrev_b32_e32 v94, 16, v67
	v_and_b32_e32 v95, 0xffff0000, v67
	v_fmac_f32_e32 v80, v96, v18
	v_fmac_f32_e32 v81, v97, v19
	v_fmac_f32_e32 v82, v98, v20
	v_fmac_f32_e32 v83, v99, v21
	v_fmac_f32_e32 v84, v100, v22
	v_fmac_f32_e32 v85, v101, v23
	v_fmac_f32_e32 v86, v102, v24
	v_fmac_f32_e32 v87, v103, v25
	v_mul_f32_e32 v104, 0x3d372713, v88
	v_mul_f32_e32 v105, 0x3d372713, v89
	v_mul_f32_e32 v106, 0x3d372713, v90
	v_mul_f32_e32 v107, 0x3d372713, v91
	v_mul_f32_e32 v108, 0x3d372713, v92
	v_mul_f32_e32 v109, 0x3d372713, v93
	v_mul_f32_e32 v110, 0x3d372713, v94
	v_mul_f32_e32 v111, 0x3d372713, v95
	v_mul_f32_e32 v104, v104, v88
	v_mul_f32_e32 v105, v105, v89
	v_mul_f32_e32 v106, v106, v90
; __device__ __forceinline__ u32x4 pack8(const float (&f)[8]) { u32x4 o; o.x = cvt_pk_bf16(f[0], f[1]); o.y = cvt_pk_bf16(f[2], f[3]); o.z = cvt_pk_bf16(f[4], f[5]); o.w = cvt_pk_bf16(f[6], f[7]); return o; }
; __device__ __forceinline__ float sigmoidf_(float x) { return __builtin_amdgcn_rcpf(1.0f + __expf(-x)); }
; __device__ __forceinline__ float gelu_tanh(float x) { return x * sigmoidf_(1.5957691216057308f * (x + 0.044715f * x * x * x)); }
; __device__ __forceinline__ void fixup_phase(KP p, int l) {
;     ...
; #pragma unroll 4
;         for (int i = 0; i < 16; ++i) {
;             const size_t m = (size_t)(m0 + i);
;             float hl[8], pc[8], gr[8], o[8], h[8];
;             unpack8(__builtin_nontemporal_load((const u32x4*)(HLOC + m * D + c0)), hl); unpack8(__builtin_nontemporal_load((const u32x4*)(PCUM + m * D + c0)), pc);
;             bf16_t* gp = P + m * DP + C_GR + c0; unpack8(*(const u32x4*)gp, gr);
; #pragma unroll
;             for (int e = 0; e < 8; ++e) { h[e] = hl[e] + pc[e] * carry[e]; o[e] = gelu_tanh(gr[e]) * h[e]; }
;             *(u32x4*)gp = pack8(o);
	v_mul_f32_e32 v107, v107, v91
	v_mul_f32_e32 v108, v108, v92
	v_mul_f32_e32 v109, v109, v93
	v_mul_f32_e32 v110, v110, v94
	v_mul_f32_e32 v111, v111, v95
	v_fma_f32 v104, v104, v88, v88
	v_fma_f32 v105, v105, v89, v89
	v_fma_f32 v106, v106, v90, v90
	v_fma_f32 v107, v107, v91, v91
	v_fma_f32 v108, v108, v92, v92
	v_fma_f32 v109, v109, v93, v93
	v_fma_f32 v110, v110, v94, v94
	v_fma_f32 v111, v111, v95, v95
	v_mul_f32_e32 v104, 0x3fcc422a, v104
	v_mul_f32_e32 v105, 0x3fcc422a, v105
	v_mul_f32_e32 v106, 0x3fcc422a, v106
	v_mul_f32_e32 v107, 0x3fcc422a, v107
	v_mul_f32_e32 v108, 0x3fcc422a, v108
	v_mul_f32_e32 v109, 0x3fcc422a, v109
	v_mul_f32_e32 v110, 0x3fcc422a, v110
	v_mul_f32_e32 v111, 0x3fcc422a, v111
	v_mul_f32_e32 v104, 0xbfb8aa3b, v104
	v_mul_f32_e32 v105, 0xbfb8aa3b, v105
	v_mul_f32_e32 v106, 0xbfb8aa3b, v106
	v_mul_f32_e32 v107, 0xbfb8aa3b, v107
	v_mul_f32_e32 v108, 0xbfb8aa3b, v108
	v_mul_f32_e32 v109, 0xbfb8aa3b, v109
	v_mul_f32_e32 v110, 0xbfb8aa3b, v110
	v_mul_f32_e32 v111, 0xbfb8aa3b, v111
	v_exp_f32_e32 v104, v104
	v_exp_f32_e32 v105, v105
	v_exp_f32_e32 v106, v106
	v_exp_f32_e32 v107, v107
	v_exp_f32_e32 v108, v108
	v_exp_f32_e32 v109, v109
	v_exp_f32_e32 v110, v110
	v_exp_f32_e32 v111, v111
	v_add_f32_e32 v104, 1.0, v104
	v_add_f32_e32 v105, 1.0, v105
	v_add_f32_e32 v106, 1.0, v106
	v_add_f32_e32 v107, 1.0, v107
	v_add_f32_e32 v108, 1.0, v108
	v_add_f32_e32 v109, 1.0, v109
	v_add_f32_e32 v110, 1.0, v110
	v_add_f32_e32 v111, 1.0, v111
	v_rcp_f32_e32 v104, v104
	v_rcp_f32_e32 v105, v105
	v_rcp_f32_e32 v106, v106
	v_rcp_f32_e32 v107, v107
	v_rcp_f32_e32 v108, v108
	v_rcp_f32_e32 v109, v109
	v_rcp_f32_e32 v110, v110
	v_rcp_f32_e32 v111, v111
	v_mul_f32_e32 v104, v104, v88
	v_mul_f32_e32 v105, v105, v89
	v_mul_f32_e32 v106, v106, v90
	v_mul_f32_e32 v107, v107, v91
	v_mul_f32_e32 v108, v108, v92
	v_mul_f32_e32 v109, v109, v93
	v_mul_f32_e32 v110, v110, v94
	v_mul_f32_e32 v111, v111, v95
	v_mul_f32_e32 v104, v80, v104
	v_mul_f32_e32 v105, v81, v105
	v_mul_f32_e32 v106, v82, v106
	v_mul_f32_e32 v107, v83, v107
	v_mul_f32_e32 v108, v84, v108
	v_mul_f32_e32 v109, v85, v109
	v_mul_f32_e32 v110, v86, v110
	v_mul_f32_e32 v111, v87, v111
	v_cvt_pk_bf16_f32 v112, v104, v105
	v_cvt_pk_bf16_f32 v113, v106, v107
	v_cvt_pk_bf16_f32 v114, v108, v109
	v_cvt_pk_bf16_f32 v115, v110, v111
	global_store_dwordx4 v27, v[112:115], s[24:25]
	s_add_u32 s24, s24, 0x2800
	s_addc_u32 s25, s25, 0
	global_load_dwordx4 v[56:59], v26, s[12:13] nt
	global_load_dwordx4 v[60:63], v26, s[14:15] nt
	global_load_dwordx4 v[64:67], v26, s[96:97]
	s_add_u32 s12, s12, 0x800
	s_addc_u32 s13, s13, 0
	s_add_u32 s14, s14, 0x800
	s_addc_u32 s15, s15, 0
	s_add_u32 s96, s96, 0x2800
	s_addc_u32 s97, s97, 0
	s_waitcnt vmcnt(12)
	v_lshlrev_b32_e32 v80, 16, v68
	v_and_b32_e32 v81, 0xffff0000, v68
	v_lshlrev_b32_e32 v82, 16, v69
	v_and_b32_e32 v83, 0xffff0000, v69
	v_lshlrev_b32_e32 v84, 16, v70
	v_and_b32_e32 v85, 0xffff0000, v70
	v_lshlrev_b32_e32 v86, 16, v71
	v_and_b32_e32 v87, 0xffff0000, v71
	v_lshlrev_b32_e32 v96, 16, v72
	v_and_b32_e32 v97, 0xffff0000, v72
	v_lshlrev_b32_e32 v98, 16, v73
	v_and_b32_e32 v99, 0xffff0000, v73
	v_lshlrev_b32_e32 v100, 16, v74
	v_and_b32_e32 v101, 0xffff0000, v74
	v_lshlrev_b32_e32 v102, 16, v75
	v_and_b32_e32 v103, 0xffff0000, v75
	v_lshlrev_b32_e32 v88, 16, v76
	v_and_b32_e32 v89, 0xffff0000, v76
	v_lshlrev_b32_e32 v90, 16, v77
	v_and_b32_e32 v91, 0xffff0000, v77
	v_lshlrev_b32_e32 v92, 16, v78
	v_and_b32_e32 v93, 0xffff0000, v78
	v_lshlrev_b32_e32 v94, 16, v79
	v_and_b32_e32 v95, 0xffff0000, v79
	v_fmac_f32_e32 v80, v96, v18
	v_fmac_f32_e32 v81, v97, v19
	v_fmac_f32_e32 v82, v98, v20
	v_fmac_f32_e32 v83, v99, v21
	v_fmac_f32_e32 v84, v100, v22
	v_fmac_f32_e32 v85, v101, v23
	v_fmac_f32_e32 v86, v102, v24
	v_fmac_f32_e32 v87, v103, v25
	v_mul_f32_e32 v104, 0x3d372713, v88
	v_mul_f32_e32 v105, 0x3d372713, v89
	v_mul_f32_e32 v106, 0x3d372713, v90
	v_mul_f32_e32 v107, 0x3d372713, v91
	v_mul_f32_e32 v108, 0x3d372713, v92
	v_mul_f32_e32 v109, 0x3d372713, v93
	v_mul_f32_e32 v110, 0x3d372713, v94
	v_mul_f32_e32 v111, 0x3d372713, v95
	v_mul_f32_e32 v104, v104, v88
	v_mul_f32_e32 v105, v105, v89
	v_mul_f32_e32 v106, v106, v90
	v_mul_f32_e32 v107, v107, v91
	v_mul_f32_e32 v108, v108, v92
	v_mul_f32_e32 v109, v109, v93
	v_mul_f32_e32 v110, v110, v94
	v_mul_f32_e32 v111, v111, v95
	v_fma_f32 v104, v104, v88, v88
	v_fma_f32 v105, v105, v89, v89
	v_fma_f32 v106, v106, v90, v90
	v_fma_f32 v107, v107, v91, v91
	v_fma_f32 v108, v108, v92, v92
	v_fma_f32 v109, v109, v93, v93
	v_fma_f32 v110, v110, v94, v94
	v_fma_f32 v111, v111, v95, v95
	v_mul_f32_e32 v104, 0x3fcc422a, v104
	v_mul_f32_e32 v105, 0x3fcc422a, v105
	v_mul_f32_e32 v106, 0x3fcc422a, v106
	v_mul_f32_e32 v107, 0x3fcc422a, v107
	v_mul_f32_e32 v108, 0x3fcc422a, v108
	v_mul_f32_e32 v109, 0x3fcc422a, v109
	v_mul_f32_e32 v110, 0x3fcc422a, v110
	v_mul_f32_e32 v111, 0x3fcc422a, v111
	v_mul_f32_e32 v104, 0xbfb8aa3b, v104
	v_mul_f32_e32 v105, 0xbfb8aa3b, v105
	v_mul_f32_e32 v106, 0xbfb8aa3b, v106
	v_mul_f32_e32 v107, 0xbfb8aa3b, v107
	v_mul_f32_e32 v108, 0xbfb8aa3b, v108
	v_mul_f32_e32 v109, 0xbfb8aa3b, v109
	v_mul_f32_e32 v110, 0xbfb8aa3b, v110
	v_mul_f32_e32 v111, 0xbfb8aa3b, v111
	v_exp_f32_e32 v104, v104
	v_exp_f32_e32 v105, v105
	v_exp_f32_e32 v106, v106
	v_exp_f32_e32 v107, v107
	v_exp_f32_e32 v108, v108
	v_exp_f32_e32 v109, v109
	v_exp_f32_e32 v110, v110
	v_exp_f32_e32 v111, v111
	v_add_f32_e32 v104, 1.0, v104
	v_add_f32_e32 v105, 1.0, v105
	v_add_f32_e32 v106, 1.0, v106
	v_add_f32_e32 v107, 1.0, v107
	v_add_f32_e32 v108, 1.0, v108
	v_add_f32_e32 v109, 1.0, v109
	v_add_f32_e32 v110, 1.0, v110
	v_add_f32_e32 v111, 1.0, v111
	v_rcp_f32_e32 v104, v104
	v_rcp_f32_e32 v105, v105
	v_rcp_f32_e32 v106, v106
	v_rcp_f32_e32 v107, v107
	v_rcp_f32_e32 v108, v108
	v_rcp_f32_e32 v109, v109
	v_rcp_f32_e32 v110, v110
	v_rcp_f32_e32 v111, v111
	v_mul_f32_e32 v104, v104, v88
	v_mul_f32_e32 v105, v105, v89
	v_mul_f32_e32 v106, v106, v90
	v_mul_f32_e32 v107, v107, v91
	v_mul_f32_e32 v108, v108, v92
	v_mul_f32_e32 v109, v109, v93
	v_mul_f32_e32 v110, v110, v94
	v_mul_f32_e32 v111, v111, v95
	v_mul_f32_e32 v104, v80, v104
	v_mul_f32_e32 v105, v81, v105
	v_mul_f32_e32 v106, v82, v106
	v_mul_f32_e32 v107, v83, v107
	v_mul_f32_e32 v108, v84, v108
	v_mul_f32_e32 v109, v85, v109
	v_mul_f32_e32 v110, v86, v110
	v_mul_f32_e32 v111, v87, v111
	v_cvt_pk_bf16_f32 v112, v104, v105
	v_cvt_pk_bf16_f32 v113, v106, v107
	v_cvt_pk_bf16_f32 v114, v108, v109
	v_cvt_pk_bf16_f32 v115, v110, v111
	global_store_dwordx4 v27, v[112:115], s[24:25]
	s_add_u32 s24, s24, 0x2800
	s_addc_u32 s25, s25, 0
	global_load_dwordx4 v[68:71], v26, s[12:13] nt
	global_load_dwordx4 v[72:75], v26, s[14:15] nt
	global_load_dwordx4 v[76:79], v26, s[96:97]
	s_add_u32 s12, s12, 0x800
	s_addc_u32 s13, s13, 0
	s_add_u32 s14, s14, 0x800
	s_addc_u32 s15, s15, 0
	s_add_u32 s96, s96, 0x2800
	s_addc_u32 s97, s97, 0
	s_waitcnt vmcnt(12)
; __device__ __forceinline__ u32x4 pack8(const float (&f)[8]) { u32x4 o; o.x = cvt_pk_bf16(f[0], f[1]); o.y = cvt_pk_bf16(f[2], f[3]); o.z = cvt_pk_bf16(f[4], f[5]); o.w = cvt_pk_bf16(f[6], f[7]); return o; }
; __device__ __forceinline__ float sigmoidf_(float x) { return __builtin_amdgcn_rcpf(1.0f + __expf(-x)); }
; __device__ __forceinline__ float gelu_tanh(float x) { return x * sigmoidf_(1.5957691216057308f * (x + 0.044715f * x * x * x)); }
; __device__ __forceinline__ void fixup_phase(KP p, int l) {
;     ...
; #pragma unroll 4
;         for (int i = 0; i < 16; ++i) {
;             const size_t m = (size_t)(m0 + i);
;             float hl[8], pc[8], gr[8], o[8], h[8];
;             unpack8(__builtin_nontemporal_load((const u32x4*)(HLOC + m * D + c0)), hl); unpack8(__builtin_nontemporal_load((const u32x4*)(PCUM + m * D + c0)), pc);
;             bf16_t* gp = P + m * DP + C_GR + c0; unpack8(*(const u32x4*)gp, gr);
; #pragma unroll
;             for (int e = 0; e < 8; ++e) { h[e] = hl[e] + pc[e] * carry[e]; o[e] = gelu_tanh(gr[e]) * h[e]; }
;             *(u32x4*)gp = pack8(o);
	v_lshlrev_b32_e32 v80, 16, v32
	v_and_b32_e32 v81, 0xffff0000, v32
	v_lshlrev_b32_e32 v82, 16, v33
	v_and_b32_e32 v83, 0xffff0000, v33
	v_lshlrev_b32_e32 v84, 16, v34
	v_and_b32_e32 v85, 0xffff0000, v34
	v_lshlrev_b32_e32 v86, 16, v35
	v_and_b32_e32 v87, 0xffff0000, v35
	v_lshlrev_b32_e32 v96, 16, v36
	v_and_b32_e32 v97, 0xffff0000, v36
	v_lshlrev_b32_e32 v98, 16, v37
	v_and_b32_e32 v99, 0xffff0000, v37
	v_lshlrev_b32_e32 v100, 16, v38
	v_and_b32_e32 v101, 0xffff0000, v38
	v_lshlrev_b32_e32 v102, 16, v39
	v_and_b32_e32 v103, 0xffff0000, v39
	v_lshlrev_b32_e32 v88, 16, v40
	v_and_b32_e32 v89, 0xffff0000, v40
	v_lshlrev_b32_e32 v90, 16, v41
	v_and_b32_e32 v91, 0xffff0000, v41
	v_lshlrev_b32_e32 v92, 16, v42
	v_and_b32_e32 v93, 0xffff0000, v42
	v_lshlrev_b32_e32 v94, 16, v43
	v_and_b32_e32 v95, 0xffff0000, v43
	v_fmac_f32_e32 v80, v96, v18
	v_fmac_f32_e32 v81, v97, v19
	v_fmac_f32_e32 v82, v98, v20
	v_fmac_f32_e32 v83, v99, v21
	v_fmac_f32_e32 v84, v100, v22
	v_fmac_f32_e32 v85, v101, v23
	v_fmac_f32_e32 v86, v102, v24
	v_fmac_f32_e32 v87, v103, v25
	v_mul_f32_e32 v104, 0x3d372713, v88
	v_mul_f32_e32 v105, 0x3d372713, v89
	v_mul_f32_e32 v106, 0x3d372713, v90
	v_mul_f32_e32 v107, 0x3d372713, v91
	v_mul_f32_e32 v108, 0x3d372713, v92
	v_mul_f32_e32 v109, 0x3d372713, v93
	v_mul_f32_e32 v110, 0x3d372713, v94
	v_mul_f32_e32 v111, 0x3d372713, v95
	v_mul_f32_e32 v104, v104, v88
	v_mul_f32_e32 v105, v105, v89
	v_mul_f32_e32 v106, v106, v90
	v_mul_f32_e32 v107, v107, v91
	v_mul_f32_e32 v108, v108, v92
	v_mul_f32_e32 v109, v109, v93
	v_mul_f32_e32 v110, v110, v94
	v_mul_f32_e32 v111, v111, v95
	v_fma_f32 v104, v104, v88, v88
	v_fma_f32 v105, v105, v89, v89
	v_fma_f32 v106, v106, v90, v90
	v_fma_f32 v107, v107, v91, v91
	v_fma_f32 v108, v108, v92, v92
	v_fma_f32 v109, v109, v93, v93
	v_fma_f32 v110, v110, v94, v94
	v_fma_f32 v111, v111, v95, v95
	v_mul_f32_e32 v104, 0x3fcc422a, v104
	v_mul_f32_e32 v105, 0x3fcc422a, v105
	v_mul_f32_e32 v106, 0x3fcc422a, v106
	v_mul_f32_e32 v107, 0x3fcc422a, v107
	v_mul_f32_e32 v108, 0x3fcc422a, v108
	v_mul_f32_e32 v109, 0x3fcc422a, v109
	v_mul_f32_e32 v110, 0x3fcc422a, v110
	v_mul_f32_e32 v111, 0x3fcc422a, v111
	v_mul_f32_e32 v104, 0xbfb8aa3b, v104
	v_mul_f32_e32 v105, 0xbfb8aa3b, v105
	v_mul_f32_e32 v106, 0xbfb8aa3b, v106
	v_mul_f32_e32 v107, 0xbfb8aa3b, v107
	v_mul_f32_e32 v108, 0xbfb8aa3b, v108
	v_mul_f32_e32 v109, 0xbfb8aa3b, v109
	v_mul_f32_e32 v110, 0xbfb8aa3b, v110
	v_mul_f32_e32 v111, 0xbfb8aa3b, v111
	v_exp_f32_e32 v104, v104
	v_exp_f32_e32 v105, v105
	v_exp_f32_e32 v106, v106
	v_exp_f32_e32 v107, v107
	v_exp_f32_e32 v108, v108
	v_exp_f32_e32 v109, v109
	v_exp_f32_e32 v110, v110
	v_exp_f32_e32 v111, v111
	v_add_f32_e32 v104, 1.0, v104
	v_add_f32_e32 v105, 1.0, v105
	v_add_f32_e32 v106, 1.0, v106
	v_add_f32_e32 v107, 1.0, v107
	v_add_f32_e32 v108, 1.0, v108
	v_add_f32_e32 v109, 1.0, v109
	v_add_f32_e32 v110, 1.0, v110
	v_add_f32_e32 v111, 1.0, v111
	v_rcp_f32_e32 v104, v104
	v_rcp_f32_e32 v105, v105
	v_rcp_f32_e32 v106, v106
	v_rcp_f32_e32 v107, v107
	v_rcp_f32_e32 v108, v108
	v_rcp_f32_e32 v109, v109
	v_rcp_f32_e32 v110, v110
	v_rcp_f32_e32 v111, v111
	v_mul_f32_e32 v104, v104, v88
	v_mul_f32_e32 v105, v105, v89
	v_mul_f32_e32 v106, v106, v90
	v_mul_f32_e32 v107, v107, v91
	v_mul_f32_e32 v108, v108, v92
	v_mul_f32_e32 v109, v109, v93
	v_mul_f32_e32 v110, v110, v94
	v_mul_f32_e32 v111, v111, v95
	v_mul_f32_e32 v104, v80, v104
	v_mul_f32_e32 v105, v81, v105
	v_mul_f32_e32 v106, v82, v106
	v_mul_f32_e32 v107, v83, v107
	v_mul_f32_e32 v108, v84, v108
	v_mul_f32_e32 v109, v85, v109
	v_mul_f32_e32 v110, v86, v110
	v_mul_f32_e32 v111, v87, v111
	v_cvt_pk_bf16_f32 v112, v104, v105
	v_cvt_pk_bf16_f32 v113, v106, v107
	v_cvt_pk_bf16_f32 v114, v108, v109
	v_cvt_pk_bf16_f32 v115, v110, v111
	global_store_dwordx4 v27, v[112:115], s[24:25]
	s_add_u32 s24, s24, 0x2800
	s_addc_u32 s25, s25, 0
	global_load_dwordx4 v[32:35], v26, s[12:13] nt
	global_load_dwordx4 v[36:39], v26, s[14:15] nt
	global_load_dwordx4 v[40:43], v26, s[96:97]
	s_add_u32 s12, s12, 0x800
	s_addc_u32 s13, s13, 0
	s_add_u32 s14, s14, 0x800
	s_addc_u32 s15, s15, 0
	s_add_u32 s96, s96, 0x2800
	s_addc_u32 s97, s97, 0
	s_waitcnt vmcnt(12)
	v_lshlrev_b32_e32 v80, 16, v44
	v_and_b32_e32 v81, 0xffff0000, v44
	v_lshlrev_b32_e32 v82, 16, v45
	v_and_b32_e32 v83, 0xffff0000, v45
	v_lshlrev_b32_e32 v84, 16, v46
	v_and_b32_e32 v85, 0xffff0000, v46
	v_lshlrev_b32_e32 v86, 16, v47
	v_and_b32_e32 v87, 0xffff0000, v47
	v_lshlrev_b32_e32 v96, 16, v48
	v_and_b32_e32 v97, 0xffff0000, v48
	v_lshlrev_b32_e32 v98, 16, v49
	v_and_b32_e32 v99, 0xffff0000, v49
	v_lshlrev_b32_e32 v100, 16, v50
	v_and_b32_e32 v101, 0xffff0000, v50
	v_lshlrev_b32_e32 v102, 16, v51
	v_and_b32_e32 v103, 0xffff0000, v51
	v_lshlrev_b32_e32 v88, 16, v52
	v_and_b32_e32 v89, 0xffff0000, v52
	v_lshlrev_b32_e32 v90, 16, v53
	v_and_b32_e32 v91, 0xffff0000, v53
	v_lshlrev_b32_e32 v92, 16, v54
	v_and_b32_e32 v93, 0xffff0000, v54
	v_lshlrev_b32_e32 v94, 16, v55
	v_and_b32_e32 v95, 0xffff0000, v55
	v_fmac_f32_e32 v80, v96, v18
	v_fmac_f32_e32 v81, v97, v19
	v_fmac_f32_e32 v82, v98, v20
	v_fmac_f32_e32 v83, v99, v21
	v_fmac_f32_e32 v84, v100, v22
	v_fmac_f32_e32 v85, v101, v23
	v_fmac_f32_e32 v86, v102, v24
	v_fmac_f32_e32 v87, v103, v25
	v_mul_f32_e32 v104, 0x3d372713, v88
	v_mul_f32_e32 v105, 0x3d372713, v89
	v_mul_f32_e32 v106, 0x3d372713, v90
	v_mul_f32_e32 v107, 0x3d372713, v91
	v_mul_f32_e32 v108, 0x3d372713, v92
	v_mul_f32_e32 v109, 0x3d372713, v93
	v_mul_f32_e32 v110, 0x3d372713, v94
	v_mul_f32_e32 v111, 0x3d372713, v95
	v_mul_f32_e32 v104, v104, v88
	v_mul_f32_e32 v105, v105, v89
	v_mul_f32_e32 v106, v106, v90
; __device__ __forceinline__ u32x4 pack8(const float (&f)[8]) { u32x4 o; o.x = cvt_pk_bf16(f[0], f[1]); o.y = cvt_pk_bf16(f[2], f[3]); o.z = cvt_pk_bf16(f[4], f[5]); o.w = cvt_pk_bf16(f[6], f[7]); return o; }
; __device__ __forceinline__ float sigmoidf_(float x) { return __builtin_amdgcn_rcpf(1.0f + __expf(-x)); }
; __device__ __forceinline__ float gelu_tanh(float x) { return x * sigmoidf_(1.5957691216057308f * (x + 0.044715f * x * x * x)); }
; __device__ __forceinline__ void fixup_phase(KP p, int l) {
;     ...
; #pragma unroll 4
;         for (int i = 0; i < 16; ++i) {
;             const size_t m = (size_t)(m0 + i);
;             float hl[8], pc[8], gr[8], o[8], h[8];
;             unpack8(__builtin_nontemporal_load((const u32x4*)(HLOC + m * D + c0)), hl); unpack8(__builtin_nontemporal_load((const u32x4*)(PCUM + m * D + c0)), pc);
;             bf16_t* gp = P + m * DP + C_GR + c0; unpack8(*(const u32x4*)gp, gr);
; #pragma unroll
;             for (int e = 0; e < 8; ++e) { h[e] = hl[e] + pc[e] * carry[e]; o[e] = gelu_tanh(gr[e]) * h[e]; }
;             *(u32x4*)gp = pack8(o);
	v_mul_f32_e32 v107, v107, v91
	v_mul_f32_e32 v108, v108, v92
	v_mul_f32_e32 v109, v109, v93
	v_mul_f32_e32 v110, v110, v94
	v_mul_f32_e32 v111, v111, v95
	v_fma_f32 v104, v104, v88, v88
	v_fma_f32 v105, v105, v89, v89
	v_fma_f32 v106, v106, v90, v90
	v_fma_f32 v107, v107, v91, v91
	v_fma_f32 v108, v108, v92, v92
	v_fma_f32 v109, v109, v93, v93
	v_fma_f32 v110, v110, v94, v94
	v_fma_f32 v111, v111, v95, v95
	v_mul_f32_e32 v104, 0x3fcc422a, v104
	v_mul_f32_e32 v105, 0x3fcc422a, v105
	v_mul_f32_e32 v106, 0x3fcc422a, v106
	v_mul_f32_e32 v107, 0x3fcc422a, v107
	v_mul_f32_e32 v108, 0x3fcc422a, v108
	v_mul_f32_e32 v109, 0x3fcc422a, v109
	v_mul_f32_e32 v110, 0x3fcc422a, v110
	v_mul_f32_e32 v111, 0x3fcc422a, v111
	v_mul_f32_e32 v104, 0xbfb8aa3b, v104
	v_mul_f32_e32 v105, 0xbfb8aa3b, v105
	v_mul_f32_e32 v106, 0xbfb8aa3b, v106
	v_mul_f32_e32 v107, 0xbfb8aa3b, v107
	v_mul_f32_e32 v108, 0xbfb8aa3b, v108
	v_mul_f32_e32 v109, 0xbfb8aa3b, v109
	v_mul_f32_e32 v110, 0xbfb8aa3b, v110
	v_mul_f32_e32 v111, 0xbfb8aa3b, v111
	v_exp_f32_e32 v104, v104
	v_exp_f32_e32 v105, v105
	v_exp_f32_e32 v106, v106
	v_exp_f32_e32 v107, v107
	v_exp_f32_e32 v108, v108
	v_exp_f32_e32 v109, v109
	v_exp_f32_e32 v110, v110
	v_exp_f32_e32 v111, v111
	v_add_f32_e32 v104, 1.0, v104
	v_add_f32_e32 v105, 1.0, v105
	v_add_f32_e32 v106, 1.0, v106
	v_add_f32_e32 v107, 1.0, v107
	v_add_f32_e32 v108, 1.0, v108
	v_add_f32_e32 v109, 1.0, v109
	v_add_f32_e32 v110, 1.0, v110
	v_add_f32_e32 v111, 1.0, v111
	v_rcp_f32_e32 v104, v104
	v_rcp_f32_e32 v105, v105
	v_rcp_f32_e32 v106, v106
	v_rcp_f32_e32 v107, v107
	v_rcp_f32_e32 v108, v108
	v_rcp_f32_e32 v109, v109
	v_rcp_f32_e32 v110, v110
	v_rcp_f32_e32 v111, v111
	v_mul_f32_e32 v104, v104, v88
	v_mul_f32_e32 v105, v105, v89
	v_mul_f32_e32 v106, v106, v90
	v_mul_f32_e32 v107, v107, v91
	v_mul_f32_e32 v108, v108, v92
	v_mul_f32_e32 v109, v109, v93
	v_mul_f32_e32 v110, v110, v94
	v_mul_f32_e32 v111, v111, v95
	v_mul_f32_e32 v104, v80, v104
	v_mul_f32_e32 v105, v81, v105
	v_mul_f32_e32 v106, v82, v106
	v_mul_f32_e32 v107, v83, v107
	v_mul_f32_e32 v108, v84, v108
	v_mul_f32_e32 v109, v85, v109
	v_mul_f32_e32 v110, v86, v110
	v_mul_f32_e32 v111, v87, v111
	v_cvt_pk_bf16_f32 v112, v104, v105
	v_cvt_pk_bf16_f32 v113, v106, v107
	v_cvt_pk_bf16_f32 v114, v108, v109
	v_cvt_pk_bf16_f32 v115, v110, v111
	global_store_dwordx4 v27, v[112:115], s[24:25]
	s_add_u32 s24, s24, 0x2800
	s_addc_u32 s25, s25, 0
	global_load_dwordx4 v[44:47], v26, s[12:13] nt
	global_load_dwordx4 v[48:51], v26, s[14:15] nt
	global_load_dwordx4 v[52:55], v26, s[96:97]
	s_add_u32 s12, s12, 0x800
	s_addc_u32 s13, s13, 0
	s_add_u32 s14, s14, 0x800
	s_addc_u32 s15, s15, 0
	s_add_u32 s96, s96, 0x2800
	s_addc_u32 s97, s97, 0
	s_waitcnt vmcnt(12)
	v_lshlrev_b32_e32 v80, 16, v56
	v_and_b32_e32 v81, 0xffff0000, v56
	v_lshlrev_b32_e32 v82, 16, v57
	v_and_b32_e32 v83, 0xffff0000, v57
	v_lshlrev_b32_e32 v84, 16, v58
	v_and_b32_e32 v85, 0xffff0000, v58
	v_lshlrev_b32_e32 v86, 16, v59
	v_and_b32_e32 v87, 0xffff0000, v59
	v_lshlrev_b32_e32 v96, 16, v60
	v_and_b32_e32 v97, 0xffff0000, v60
	v_lshlrev_b32_e32 v98, 16, v61
	v_and_b32_e32 v99, 0xffff0000, v61
	v_lshlrev_b32_e32 v100, 16, v62
	v_and_b32_e32 v101, 0xffff0000, v62
	v_lshlrev_b32_e32 v102, 16, v63
	v_and_b32_e32 v103, 0xffff0000, v63
	v_lshlrev_b32_e32 v88, 16, v64
	v_and_b32_e32 v89, 0xffff0000, v64
	v_lshlrev_b32_e32 v90, 16, v65
	v_and_b32_e32 v91, 0xffff0000, v65
	v_lshlrev_b32_e32 v92, 16, v66
	v_and_b32_e32 v93, 0xffff0000, v66
	v_lshlrev_b32_e32 v94, 16, v67
	v_and_b32_e32 v95, 0xffff0000, v67
	v_fmac_f32_e32 v80, v96, v18
	v_fmac_f32_e32 v81, v97, v19
	v_fmac_f32_e32 v82, v98, v20
	v_fmac_f32_e32 v83, v99, v21
	v_fmac_f32_e32 v84, v100, v22
	v_fmac_f32_e32 v85, v101, v23
	v_fmac_f32_e32 v86, v102, v24
	v_fmac_f32_e32 v87, v103, v25
	v_mul_f32_e32 v104, 0x3d372713, v88
	v_mul_f32_e32 v105, 0x3d372713, v89
	v_mul_f32_e32 v106, 0x3d372713, v90
	v_mul_f32_e32 v107, 0x3d372713, v91
	v_mul_f32_e32 v108, 0x3d372713, v92
	v_mul_f32_e32 v109, 0x3d372713, v93
	v_mul_f32_e32 v110, 0x3d372713, v94
	v_mul_f32_e32 v111, 0x3d372713, v95
	v_mul_f32_e32 v104, v104, v88
	v_mul_f32_e32 v105, v105, v89
	v_mul_f32_e32 v106, v106, v90
	v_mul_f32_e32 v107, v107, v91
	v_mul_f32_e32 v108, v108, v92
	v_mul_f32_e32 v109, v109, v93
	v_mul_f32_e32 v110, v110, v94
	v_mul_f32_e32 v111, v111, v95
	v_fma_f32 v104, v104, v88, v88
	v_fma_f32 v105, v105, v89, v89
	v_fma_f32 v106, v106, v90, v90
	v_fma_f32 v107, v107, v91, v91
	v_fma_f32 v108, v108, v92, v92
	v_fma_f32 v109, v109, v93, v93
	v_fma_f32 v110, v110, v94, v94
	v_fma_f32 v111, v111, v95, v95
	v_mul_f32_e32 v104, 0x3fcc422a, v104
	v_mul_f32_e32 v105, 0x3fcc422a, v105
	v_mul_f32_e32 v106, 0x3fcc422a, v106
	v_mul_f32_e32 v107, 0x3fcc422a, v107
	v_mul_f32_e32 v108, 0x3fcc422a, v108
	v_mul_f32_e32 v109, 0x3fcc422a, v109
	v_mul_f32_e32 v110, 0x3fcc422a, v110
	v_mul_f32_e32 v111, 0x3fcc422a, v111
	v_mul_f32_e32 v104, 0xbfb8aa3b, v104
	v_mul_f32_e32 v105, 0xbfb8aa3b, v105
	v_mul_f32_e32 v106, 0xbfb8aa3b, v106
	v_mul_f32_e32 v107, 0xbfb8aa3b, v107
	v_mul_f32_e32 v108, 0xbfb8aa3b, v108
	v_mul_f32_e32 v109, 0xbfb8aa3b, v109
	v_mul_f32_e32 v110, 0xbfb8aa3b, v110
	v_mul_f32_e32 v111, 0xbfb8aa3b, v111
	v_exp_f32_e32 v104, v104
	v_exp_f32_e32 v105, v105
	v_exp_f32_e32 v106, v106
	v_exp_f32_e32 v107, v107
	v_exp_f32_e32 v108, v108
	v_exp_f32_e32 v109, v109
	v_exp_f32_e32 v110, v110
	v_exp_f32_e32 v111, v111
	v_add_f32_e32 v104, 1.0, v104
	v_add_f32_e32 v105, 1.0, v105
	v_add_f32_e32 v106, 1.0, v106
	v_add_f32_e32 v107, 1.0, v107
	v_add_f32_e32 v108, 1.0, v108
	v_add_f32_e32 v109, 1.0, v109
	v_add_f32_e32 v110, 1.0, v110
	v_add_f32_e32 v111, 1.0, v111
	v_rcp_f32_e32 v104, v104
	v_rcp_f32_e32 v105, v105
	v_rcp_f32_e32 v106, v106
	v_rcp_f32_e32 v107, v107
	v_rcp_f32_e32 v108, v108
	v_rcp_f32_e32 v109, v109
	v_rcp_f32_e32 v110, v110
	v_rcp_f32_e32 v111, v111
	v_mul_f32_e32 v104, v104, v88
	v_mul_f32_e32 v105, v105, v89
	v_mul_f32_e32 v106, v106, v90
	v_mul_f32_e32 v107, v107, v91
	v_mul_f32_e32 v108, v108, v92
	v_mul_f32_e32 v109, v109, v93
	v_mul_f32_e32 v110, v110, v94
	v_mul_f32_e32 v111, v111, v95
	v_mul_f32_e32 v104, v80, v104
	v_mul_f32_e32 v105, v81, v105
	v_mul_f32_e32 v106, v82, v106
	v_mul_f32_e32 v107, v83, v107
	v_mul_f32_e32 v108, v84, v108
	v_mul_f32_e32 v109, v85, v109
	v_mul_f32_e32 v110, v86, v110
	v_mul_f32_e32 v111, v87, v111
	v_cvt_pk_bf16_f32 v112, v104, v105
	v_cvt_pk_bf16_f32 v113, v106, v107
	v_cvt_pk_bf16_f32 v114, v108, v109
	v_cvt_pk_bf16_f32 v115, v110, v111
	global_store_dwordx4 v27, v[112:115], s[24:25]
	s_add_u32 s24, s24, 0x2800
	s_addc_u32 s25, s25, 0
	global_load_dwordx4 v[56:59], v26, s[12:13] nt
	global_load_dwordx4 v[60:63], v26, s[14:15] nt
	global_load_dwordx4 v[64:67], v26, s[96:97]
	s_add_u32 s12, s12, 0x800
	s_addc_u32 s13, s13, 0
	s_add_u32 s14, s14, 0x800
	s_addc_u32 s15, s15, 0
	s_add_u32 s96, s96, 0x2800
	s_addc_u32 s97, s97, 0
	s_waitcnt vmcnt(12)
; __device__ __forceinline__ u32x4 pack8(const float (&f)[8]) { u32x4 o; o.x = cvt_pk_bf16(f[0], f[1]); o.y = cvt_pk_bf16(f[2], f[3]); o.z = cvt_pk_bf16(f[4], f[5]); o.w = cvt_pk_bf16(f[6], f[7]); return o; }
; __device__ __forceinline__ float sigmoidf_(float x) { return __builtin_amdgcn_rcpf(1.0f + __expf(-x)); }
; __device__ __forceinline__ float gelu_tanh(float x) { return x * sigmoidf_(1.5957691216057308f * (x + 0.044715f * x * x * x)); }
; __device__ __forceinline__ void fixup_phase(KP p, int l) {
;     ...
; #pragma unroll 4
;         for (int i = 0; i < 16; ++i) {
;             const size_t m = (size_t)(m0 + i);
;             float hl[8], pc[8], gr[8], o[8], h[8];
;             unpack8(__builtin_nontemporal_load((const u32x4*)(HLOC + m * D + c0)), hl); unpack8(__builtin_nontemporal_load((const u32x4*)(PCUM + m * D + c0)), pc);
;             bf16_t* gp = P + m * DP + C_GR + c0; unpack8(*(const u32x4*)gp, gr);
; #pragma unroll
;             for (int e = 0; e < 8; ++e) { h[e] = hl[e] + pc[e] * carry[e]; o[e] = gelu_tanh(gr[e]) * h[e]; }
;             *(u32x4*)gp = pack8(o);
	v_lshlrev_b32_e32 v80, 16, v68
	v_and_b32_e32 v81, 0xffff0000, v68
	v_lshlrev_b32_e32 v82, 16, v69
	v_and_b32_e32 v83, 0xffff0000, v69
	v_lshlrev_b32_e32 v84, 16, v70
	v_and_b32_e32 v85, 0xffff0000, v70
	v_lshlrev_b32_e32 v86, 16, v71
	v_and_b32_e32 v87, 0xffff0000, v71
	v_lshlrev_b32_e32 v96, 16, v72
	v_and_b32_e32 v97, 0xffff0000, v72
	v_lshlrev_b32_e32 v98, 16, v73
	v_and_b32_e32 v99, 0xffff0000, v73
	v_lshlrev_b32_e32 v100, 16, v74
	v_and_b32_e32 v101, 0xffff0000, v74
	v_lshlrev_b32_e32 v102, 16, v75
	v_and_b32_e32 v103, 0xffff0000, v75
	v_lshlrev_b32_e32 v88, 16, v76
	v_and_b32_e32 v89, 0xffff0000, v76
	v_lshlrev_b32_e32 v90, 16, v77
	v_and_b32_e32 v91, 0xffff0000, v77
	v_lshlrev_b32_e32 v92, 16, v78
	v_and_b32_e32 v93, 0xffff0000, v78
	v_lshlrev_b32_e32 v94, 16, v79
	v_and_b32_e32 v95, 0xffff0000, v79
	v_fmac_f32_e32 v80, v96, v18
	v_fmac_f32_e32 v81, v97, v19
	v_fmac_f32_e32 v82, v98, v20
	v_fmac_f32_e32 v83, v99, v21
	v_fmac_f32_e32 v84, v100, v22
	v_fmac_f32_e32 v85, v101, v23
	v_fmac_f32_e32 v86, v102, v24
	v_fmac_f32_e32 v87, v103, v25
	v_mul_f32_e32 v104, 0x3d372713, v88
	v_mul_f32_e32 v105, 0x3d372713, v89
	v_mul_f32_e32 v106, 0x3d372713, v90
	v_mul_f32_e32 v107, 0x3d372713, v91
	v_mul_f32_e32 v108, 0x3d372713, v92
	v_mul_f32_e32 v109, 0x3d372713, v93
	v_mul_f32_e32 v110, 0x3d372713, v94
	v_mul_f32_e32 v111, 0x3d372713, v95
	v_mul_f32_e32 v104, v104, v88
	v_mul_f32_e32 v105, v105, v89
	v_mul_f32_e32 v106, v106, v90
	v_mul_f32_e32 v107, v107, v91
	v_mul_f32_e32 v108, v108, v92
	v_mul_f32_e32 v109, v109, v93
	v_mul_f32_e32 v110, v110, v94
	v_mul_f32_e32 v111, v111, v95
	v_fma_f32 v104, v104, v88, v88
	v_fma_f32 v105, v105, v89, v89
	v_fma_f32 v106, v106, v90, v90
	v_fma_f32 v107, v107, v91, v91
	v_fma_f32 v108, v108, v92, v92
	v_fma_f32 v109, v109, v93, v93
	v_fma_f32 v110, v110, v94, v94
	v_fma_f32 v111, v111, v95, v95
	v_mul_f32_e32 v104, 0x3fcc422a, v104
	v_mul_f32_e32 v105, 0x3fcc422a, v105
	v_mul_f32_e32 v106, 0x3fcc422a, v106
	v_mul_f32_e32 v107, 0x3fcc422a, v107
	v_mul_f32_e32 v108, 0x3fcc422a, v108
	v_mul_f32_e32 v109, 0x3fcc422a, v109
	v_mul_f32_e32 v110, 0x3fcc422a, v110
	v_mul_f32_e32 v111, 0x3fcc422a, v111
	v_mul_f32_e32 v104, 0xbfb8aa3b, v104
	v_mul_f32_e32 v105, 0xbfb8aa3b, v105
	v_mul_f32_e32 v106, 0xbfb8aa3b, v106
	v_mul_f32_e32 v107, 0xbfb8aa3b, v107
	v_mul_f32_e32 v108, 0xbfb8aa3b, v108
	v_mul_f32_e32 v109, 0xbfb8aa3b, v109
	v_mul_f32_e32 v110, 0xbfb8aa3b, v110
	v_mul_f32_e32 v111, 0xbfb8aa3b, v111
	v_exp_f32_e32 v104, v104
	v_exp_f32_e32 v105, v105
	v_exp_f32_e32 v106, v106
	v_exp_f32_e32 v107, v107
	v_exp_f32_e32 v108, v108
	v_exp_f32_e32 v109, v109
	v_exp_f32_e32 v110, v110
	v_exp_f32_e32 v111, v111
	v_add_f32_e32 v104, 1.0, v104
	v_add_f32_e32 v105, 1.0, v105
	v_add_f32_e32 v106, 1.0, v106
	v_add_f32_e32 v107, 1.0, v107
	v_add_f32_e32 v108, 1.0, v108
	v_add_f32_e32 v109, 1.0, v109
	v_add_f32_e32 v110, 1.0, v110
	v_add_f32_e32 v111, 1.0, v111
	v_rcp_f32_e32 v104, v104
	v_rcp_f32_e32 v105, v105
	v_rcp_f32_e32 v106, v106
	v_rcp_f32_e32 v107, v107
	v_rcp_f32_e32 v108, v108
	v_rcp_f32_e32 v109, v109
	v_rcp_f32_e32 v110, v110
	v_rcp_f32_e32 v111, v111
	v_mul_f32_e32 v104, v104, v88
	v_mul_f32_e32 v105, v105, v89
	v_mul_f32_e32 v106, v106, v90
	v_mul_f32_e32 v107, v107, v91
	v_mul_f32_e32 v108, v108, v92
	v_mul_f32_e32 v109, v109, v93
	v_mul_f32_e32 v110, v110, v94
	v_mul_f32_e32 v111, v111, v95
	v_mul_f32_e32 v104, v80, v104
	v_mul_f32_e32 v105, v81, v105
	v_mul_f32_e32 v106, v82, v106
	v_mul_f32_e32 v107, v83, v107
	v_mul_f32_e32 v108, v84, v108
	v_mul_f32_e32 v109, v85, v109
	v_mul_f32_e32 v110, v86, v110
	v_mul_f32_e32 v111, v87, v111
	v_cvt_pk_bf16_f32 v112, v104, v105
	v_cvt_pk_bf16_f32 v113, v106, v107
	v_cvt_pk_bf16_f32 v114, v108, v109
	v_cvt_pk_bf16_f32 v115, v110, v111
	global_store_dwordx4 v27, v[112:115], s[24:25]
	s_add_u32 s24, s24, 0x2800
	s_addc_u32 s25, s25, 0
	global_load_dwordx4 v[68:71], v26, s[12:13] nt
	global_load_dwordx4 v[72:75], v26, s[14:15] nt
	global_load_dwordx4 v[76:79], v26, s[96:97]
	s_add_u32 s12, s12, 0x800
	s_addc_u32 s13, s13, 0
	s_add_u32 s14, s14, 0x800
	s_addc_u32 s15, s15, 0
	s_add_u32 s96, s96, 0x2800
	s_addc_u32 s97, s97, 0
	s_waitcnt vmcnt(12)
	v_lshlrev_b32_e32 v80, 16, v32
	v_and_b32_e32 v81, 0xffff0000, v32
	v_lshlrev_b32_e32 v82, 16, v33
	v_and_b32_e32 v83, 0xffff0000, v33
	v_lshlrev_b32_e32 v84, 16, v34
	v_and_b32_e32 v85, 0xffff0000, v34
	v_lshlrev_b32_e32 v86, 16, v35
	v_and_b32_e32 v87, 0xffff0000, v35
	v_lshlrev_b32_e32 v96, 16, v36
	v_and_b32_e32 v97, 0xffff0000, v36
	v_lshlrev_b32_e32 v98, 16, v37
	v_and_b32_e32 v99, 0xffff0000, v37
	v_lshlrev_b32_e32 v100, 16, v38
	v_and_b32_e32 v101, 0xffff0000, v38
	v_lshlrev_b32_e32 v102, 16, v39
	v_and_b32_e32 v103, 0xffff0000, v39
	v_lshlrev_b32_e32 v88, 16, v40
	v_and_b32_e32 v89, 0xffff0000, v40
	v_lshlrev_b32_e32 v90, 16, v41
	v_and_b32_e32 v91, 0xffff0000, v41
	v_lshlrev_b32_e32 v92, 16, v42
	v_and_b32_e32 v93, 0xffff0000, v42
	v_lshlrev_b32_e32 v94, 16, v43
	v_and_b32_e32 v95, 0xffff0000, v43
	v_fmac_f32_e32 v80, v96, v18
	v_fmac_f32_e32 v81, v97, v19
	v_fmac_f32_e32 v82, v98, v20
	v_fmac_f32_e32 v83, v99, v21
	v_fmac_f32_e32 v84, v100, v22
	v_fmac_f32_e32 v85, v101, v23
	v_fmac_f32_e32 v86, v102, v24
	v_fmac_f32_e32 v87, v103, v25
	v_mul_f32_e32 v104, 0x3d372713, v88
	v_mul_f32_e32 v105, 0x3d372713, v89
	v_mul_f32_e32 v106, 0x3d372713, v90
	v_mul_f32_e32 v107, 0x3d372713, v91
	v_mul_f32_e32 v108, 0x3d372713, v92
	v_mul_f32_e32 v109, 0x3d372713, v93
	v_mul_f32_e32 v110, 0x3d372713, v94
	v_mul_f32_e32 v111, 0x3d372713, v95
	v_mul_f32_e32 v104, v104, v88
	v_mul_f32_e32 v105, v105, v89
	v_mul_f32_e32 v106, v106, v90
; __device__ __forceinline__ u32x4 pack8(const float (&f)[8]) { u32x4 o; o.x = cvt_pk_bf16(f[0], f[1]); o.y = cvt_pk_bf16(f[2], f[3]); o.z = cvt_pk_bf16(f[4], f[5]); o.w = cvt_pk_bf16(f[6], f[7]); return o; }
; __device__ __forceinline__ float sigmoidf_(float x) { return __builtin_amdgcn_rcpf(1.0f + __expf(-x)); }
; __device__ __forceinline__ float gelu_tanh(float x) { return x * sigmoidf_(1.5957691216057308f * (x + 0.044715f * x * x * x)); }
; __device__ __forceinline__ void fixup_phase(KP p, int l) {
;     ...
; #pragma unroll 4
;         for (int i = 0; i < 16; ++i) {
;             const size_t m = (size_t)(m0 + i);
;             float hl[8], pc[8], gr[8], o[8], h[8];
;             unpack8(__builtin_nontemporal_load((const u32x4*)(HLOC + m * D + c0)), hl); unpack8(__builtin_nontemporal_load((const u32x4*)(PCUM + m * D + c0)), pc);
;             bf16_t* gp = P + m * DP + C_GR + c0; unpack8(*(const u32x4*)gp, gr);
; #pragma unroll
;             for (int e = 0; e < 8; ++e) { h[e] = hl[e] + pc[e] * carry[e]; o[e] = gelu_tanh(gr[e]) * h[e]; }
;             *(u32x4*)gp = pack8(o);
	v_mul_f32_e32 v107, v107, v91
	v_mul_f32_e32 v108, v108, v92
	v_mul_f32_e32 v109, v109, v93
	v_mul_f32_e32 v110, v110, v94
	v_mul_f32_e32 v111, v111, v95
	v_fma_f32 v104, v104, v88, v88
	v_fma_f32 v105, v105, v89, v89
	v_fma_f32 v106, v106, v90, v90
	v_fma_f32 v107, v107, v91, v91
	v_fma_f32 v108, v108, v92, v92
	v_fma_f32 v109, v109, v93, v93
	v_fma_f32 v110, v110, v94, v94
	v_fma_f32 v111, v111, v95, v95
	v_mul_f32_e32 v104, 0x3fcc422a, v104
	v_mul_f32_e32 v105, 0x3fcc422a, v105
	v_mul_f32_e32 v106, 0x3fcc422a, v106
	v_mul_f32_e32 v107, 0x3fcc422a, v107
	v_mul_f32_e32 v108, 0x3fcc422a, v108
	v_mul_f32_e32 v109, 0x3fcc422a, v109
	v_mul_f32_e32 v110, 0x3fcc422a, v110
	v_mul_f32_e32 v111, 0x3fcc422a, v111
	v_mul_f32_e32 v104, 0xbfb8aa3b, v104
	v_mul_f32_e32 v105, 0xbfb8aa3b, v105
	v_mul_f32_e32 v106, 0xbfb8aa3b, v106
	v_mul_f32_e32 v107, 0xbfb8aa3b, v107
	v_mul_f32_e32 v108, 0xbfb8aa3b, v108
	v_mul_f32_e32 v109, 0xbfb8aa3b, v109
	v_mul_f32_e32 v110, 0xbfb8aa3b, v110
	v_mul_f32_e32 v111, 0xbfb8aa3b, v111
	v_exp_f32_e32 v104, v104
	v_exp_f32_e32 v105, v105
	v_exp_f32_e32 v106, v106
	v_exp_f32_e32 v107, v107
	v_exp_f32_e32 v108, v108
	v_exp_f32_e32 v109, v109
	v_exp_f32_e32 v110, v110
	v_exp_f32_e32 v111, v111
	v_add_f32_e32 v104, 1.0, v104
	v_add_f32_e32 v105, 1.0, v105
	v_add_f32_e32 v106, 1.0, v106
	v_add_f32_e32 v107, 1.0, v107
	v_add_f32_e32 v108, 1.0, v108
	v_add_f32_e32 v109, 1.0, v109
	v_add_f32_e32 v110, 1.0, v110
	v_add_f32_e32 v111, 1.0, v111
	v_rcp_f32_e32 v104, v104
	v_rcp_f32_e32 v105, v105
	v_rcp_f32_e32 v106, v106
	v_rcp_f32_e32 v107, v107
	v_rcp_f32_e32 v108, v108
	v_rcp_f32_e32 v109, v109
	v_rcp_f32_e32 v110, v110
	v_rcp_f32_e32 v111, v111
	v_mul_f32_e32 v104, v104, v88
	v_mul_f32_e32 v105, v105, v89
	v_mul_f32_e32 v106, v106, v90
	v_mul_f32_e32 v107, v107, v91
	v_mul_f32_e32 v108, v108, v92
	v_mul_f32_e32 v109, v109, v93
	v_mul_f32_e32 v110, v110, v94
	v_mul_f32_e32 v111, v111, v95
	v_mul_f32_e32 v104, v80, v104
	v_mul_f32_e32 v105, v81, v105
	v_mul_f32_e32 v106, v82, v106
	v_mul_f32_e32 v107, v83, v107
	v_mul_f32_e32 v108, v84, v108
	v_mul_f32_e32 v109, v85, v109
	v_mul_f32_e32 v110, v86, v110
	v_mul_f32_e32 v111, v87, v111
	v_cvt_pk_bf16_f32 v112, v104, v105
	v_cvt_pk_bf16_f32 v113, v106, v107
	v_cvt_pk_bf16_f32 v114, v108, v109
	v_cvt_pk_bf16_f32 v115, v110, v111
	global_store_dwordx4 v27, v[112:115], s[24:25]
	s_add_u32 s24, s24, 0x2800
	s_addc_u32 s25, s25, 0
	global_load_dwordx4 v[32:35], v26, s[12:13] nt
	global_load_dwordx4 v[36:39], v26, s[14:15] nt
	global_load_dwordx4 v[40:43], v26, s[96:97]
	s_add_u32 s12, s12, 0x800
	s_addc_u32 s13, s13, 0
	s_add_u32 s14, s14, 0x800
	s_addc_u32 s15, s15, 0
	s_add_u32 s96, s96, 0x2800
	s_addc_u32 s97, s97, 0
	s_waitcnt vmcnt(12)
	v_lshlrev_b32_e32 v80, 16, v44
	v_and_b32_e32 v81, 0xffff0000, v44
	v_lshlrev_b32_e32 v82, 16, v45
	v_and_b32_e32 v83, 0xffff0000, v45
	v_lshlrev_b32_e32 v84, 16, v46
	v_and_b32_e32 v85, 0xffff0000, v46
	v_lshlrev_b32_e32 v86, 16, v47
	v_and_b32_e32 v87, 0xffff0000, v47
	v_lshlrev_b32_e32 v96, 16, v48
	v_and_b32_e32 v97, 0xffff0000, v48
	v_lshlrev_b32_e32 v98, 16, v49
	v_and_b32_e32 v99, 0xffff0000, v49
	v_lshlrev_b32_e32 v100, 16, v50
	v_and_b32_e32 v101, 0xffff0000, v50
	v_lshlrev_b32_e32 v102, 16, v51
	v_and_b32_e32 v103, 0xffff0000, v51
	v_lshlrev_b32_e32 v88, 16, v52
	v_and_b32_e32 v89, 0xffff0000, v52
	v_lshlrev_b32_e32 v90, 16, v53
	v_and_b32_e32 v91, 0xffff0000, v53
	v_lshlrev_b32_e32 v92, 16, v54
	v_and_b32_e32 v93, 0xffff0000, v54
	v_lshlrev_b32_e32 v94, 16, v55
	v_and_b32_e32 v95, 0xffff0000, v55
	v_fmac_f32_e32 v80, v96, v18
	v_fmac_f32_e32 v81, v97, v19
	v_fmac_f32_e32 v82, v98, v20
	v_fmac_f32_e32 v83, v99, v21
	v_fmac_f32_e32 v84, v100, v22
	v_fmac_f32_e32 v85, v101, v23
	v_fmac_f32_e32 v86, v102, v24
	v_fmac_f32_e32 v87, v103, v25
	v_mul_f32_e32 v104, 0x3d372713, v88
	v_mul_f32_e32 v105, 0x3d372713, v89
	v_mul_f32_e32 v106, 0x3d372713, v90
	v_mul_f32_e32 v107, 0x3d372713, v91
	v_mul_f32_e32 v108, 0x3d372713, v92
	v_mul_f32_e32 v109, 0x3d372713, v93
	v_mul_f32_e32 v110, 0x3d372713, v94
	v_mul_f32_e32 v111, 0x3d372713, v95
	v_mul_f32_e32 v104, v104, v88
	v_mul_f32_e32 v105, v105, v89
	v_mul_f32_e32 v106, v106, v90
	v_mul_f32_e32 v107, v107, v91
	v_mul_f32_e32 v108, v108, v92
	v_mul_f32_e32 v109, v109, v93
	v_mul_f32_e32 v110, v110, v94
	v_mul_f32_e32 v111, v111, v95
	v_fma_f32 v104, v104, v88, v88
	v_fma_f32 v105, v105, v89, v89
	v_fma_f32 v106, v106, v90, v90
	v_fma_f32 v107, v107, v91, v91
	v_fma_f32 v108, v108, v92, v92
	v_fma_f32 v109, v109, v93, v93
	v_fma_f32 v110, v110, v94, v94
	v_fma_f32 v111, v111, v95, v95
	v_mul_f32_e32 v104, 0x3fcc422a, v104
	v_mul_f32_e32 v105, 0x3fcc422a, v105
	v_mul_f32_e32 v106, 0x3fcc422a, v106
	v_mul_f32_e32 v107, 0x3fcc422a, v107
	v_mul_f32_e32 v108, 0x3fcc422a, v108
	v_mul_f32_e32 v109, 0x3fcc422a, v109
	v_mul_f32_e32 v110, 0x3fcc422a, v110
	v_mul_f32_e32 v111, 0x3fcc422a, v111
	v_mul_f32_e32 v104, 0xbfb8aa3b, v104
	v_mul_f32_e32 v105, 0xbfb8aa3b, v105
	v_mul_f32_e32 v106, 0xbfb8aa3b, v106
	v_mul_f32_e32 v107, 0xbfb8aa3b, v107
	v_mul_f32_e32 v108, 0xbfb8aa3b, v108
	v_mul_f32_e32 v109, 0xbfb8aa3b, v109
	v_mul_f32_e32 v110, 0xbfb8aa3b, v110
	v_mul_f32_e32 v111, 0xbfb8aa3b, v111
	v_exp_f32_e32 v104, v104
	v_exp_f32_e32 v105, v105
	v_exp_f32_e32 v106, v106
	v_exp_f32_e32 v107, v107
	v_exp_f32_e32 v108, v108
	v_exp_f32_e32 v109, v109
	v_exp_f32_e32 v110, v110
	v_exp_f32_e32 v111, v111
	v_add_f32_e32 v104, 1.0, v104
	v_add_f32_e32 v105, 1.0, v105
	v_add_f32_e32 v106, 1.0, v106
	v_add_f32_e32 v107, 1.0, v107
	v_add_f32_e32 v108, 1.0, v108
	v_add_f32_e32 v109, 1.0, v109
	v_add_f32_e32 v110, 1.0, v110
	v_add_f32_e32 v111, 1.0, v111
	v_rcp_f32_e32 v104, v104
	v_rcp_f32_e32 v105, v105
	v_rcp_f32_e32 v106, v106
	v_rcp_f32_e32 v107, v107
	v_rcp_f32_e32 v108, v108
	v_rcp_f32_e32 v109, v109
	v_rcp_f32_e32 v110, v110
	v_rcp_f32_e32 v111, v111
	v_mul_f32_e32 v104, v104, v88
	v_mul_f32_e32 v105, v105, v89
	v_mul_f32_e32 v106, v106, v90
	v_mul_f32_e32 v107, v107, v91
	v_mul_f32_e32 v108, v108, v92
	v_mul_f32_e32 v109, v109, v93
	v_mul_f32_e32 v110, v110, v94
	v_mul_f32_e32 v111, v111, v95
	v_mul_f32_e32 v104, v80, v104
	v_mul_f32_e32 v105, v81, v105
	v_mul_f32_e32 v106, v82, v106
	v_mul_f32_e32 v107, v83, v107
	v_mul_f32_e32 v108, v84, v108
	v_mul_f32_e32 v109, v85, v109
	v_mul_f32_e32 v110, v86, v110
	v_mul_f32_e32 v111, v87, v111
	v_cvt_pk_bf16_f32 v112, v104, v105
	v_cvt_pk_bf16_f32 v113, v106, v107
	v_cvt_pk_bf16_f32 v114, v108, v109
	v_cvt_pk_bf16_f32 v115, v110, v111
	global_store_dwordx4 v27, v[112:115], s[24:25]
	s_add_u32 s24, s24, 0x2800
	s_addc_u32 s25, s25, 0
	global_load_dwordx4 v[44:47], v26, s[12:13] nt
	global_load_dwordx4 v[48:51], v26, s[14:15] nt
	global_load_dwordx4 v[52:55], v26, s[96:97]
	s_add_u32 s12, s12, 0x800
	s_addc_u32 s13, s13, 0
	s_add_u32 s14, s14, 0x800
	s_addc_u32 s15, s15, 0
	s_add_u32 s96, s96, 0x2800
	s_addc_u32 s97, s97, 0
	s_waitcnt vmcnt(12)
; __device__ __forceinline__ u32x4 pack8(const float (&f)[8]) { u32x4 o; o.x = cvt_pk_bf16(f[0], f[1]); o.y = cvt_pk_bf16(f[2], f[3]); o.z = cvt_pk_bf16(f[4], f[5]); o.w = cvt_pk_bf16(f[6], f[7]); return o; }
; __device__ __forceinline__ float sigmoidf_(float x) { return __builtin_amdgcn_rcpf(1.0f + __expf(-x)); }
; __device__ __forceinline__ float gelu_tanh(float x) { return x * sigmoidf_(1.5957691216057308f * (x + 0.044715f * x * x * x)); }
; __device__ __forceinline__ void fixup_phase(KP p, int l) {
;     ...
; #pragma unroll 4
;         for (int i = 0; i < 16; ++i) {
;             const size_t m = (size_t)(m0 + i);
;             float hl[8], pc[8], gr[8], o[8], h[8];
;             unpack8(__builtin_nontemporal_load((const u32x4*)(HLOC + m * D + c0)), hl); unpack8(__builtin_nontemporal_load((const u32x4*)(PCUM + m * D + c0)), pc);
;             bf16_t* gp = P + m * DP + C_GR + c0; unpack8(*(const u32x4*)gp, gr);
; #pragma unroll
;             for (int e = 0; e < 8; ++e) { h[e] = hl[e] + pc[e] * carry[e]; o[e] = gelu_tanh(gr[e]) * h[e]; }
;             *(u32x4*)gp = pack8(o);
	v_lshlrev_b32_e32 v80, 16, v56
	v_and_b32_e32 v81, 0xffff0000, v56
	v_lshlrev_b32_e32 v82, 16, v57
	v_and_b32_e32 v83, 0xffff0000, v57
	v_lshlrev_b32_e32 v84, 16, v58
	v_and_b32_e32 v85, 0xffff0000, v58
	v_lshlrev_b32_e32 v86, 16, v59
	v_and_b32_e32 v87, 0xffff0000, v59
	v_lshlrev_b32_e32 v96, 16, v60
	v_and_b32_e32 v97, 0xffff0000, v60
	v_lshlrev_b32_e32 v98, 16, v61
	v_and_b32_e32 v99, 0xffff0000, v61
	v_lshlrev_b32_e32 v100, 16, v62
	v_and_b32_e32 v101, 0xffff0000, v62
	v_lshlrev_b32_e32 v102, 16, v63
	v_and_b32_e32 v103, 0xffff0000, v63
	v_lshlrev_b32_e32 v88, 16, v64
	v_and_b32_e32 v89, 0xffff0000, v64
	v_lshlrev_b32_e32 v90, 16, v65
	v_and_b32_e32 v91, 0xffff0000, v65
	v_lshlrev_b32_e32 v92, 16, v66
	v_and_b32_e32 v93, 0xffff0000, v66
	v_lshlrev_b32_e32 v94, 16, v67
	v_and_b32_e32 v95, 0xffff0000, v67
	v_fmac_f32_e32 v80, v96, v18
	v_fmac_f32_e32 v81, v97, v19
	v_fmac_f32_e32 v82, v98, v20
	v_fmac_f32_e32 v83, v99, v21
	v_fmac_f32_e32 v84, v100, v22
	v_fmac_f32_e32 v85, v101, v23
	v_fmac_f32_e32 v86, v102, v24
	v_fmac_f32_e32 v87, v103, v25
	v_mul_f32_e32 v104, 0x3d372713, v88
	v_mul_f32_e32 v105, 0x3d372713, v89
	v_mul_f32_e32 v106, 0x3d372713, v90
	v_mul_f32_e32 v107, 0x3d372713, v91
	v_mul_f32_e32 v108, 0x3d372713, v92
	v_mul_f32_e32 v109, 0x3d372713, v93
	v_mul_f32_e32 v110, 0x3d372713, v94
	v_mul_f32_e32 v111, 0x3d372713, v95
	v_mul_f32_e32 v104, v104, v88
	v_mul_f32_e32 v105, v105, v89
	v_mul_f32_e32 v106, v106, v90
	v_mul_f32_e32 v107, v107, v91
	v_mul_f32_e32 v108, v108, v92
	v_mul_f32_e32 v109, v109, v93
	v_mul_f32_e32 v110, v110, v94
	v_mul_f32_e32 v111, v111, v95
	v_fma_f32 v104, v104, v88, v88
	v_fma_f32 v105, v105, v89, v89
	v_fma_f32 v106, v106, v90, v90
	v_fma_f32 v107, v107, v91, v91
	v_fma_f32 v108, v108, v92, v92
	v_fma_f32 v109, v109, v93, v93
	v_fma_f32 v110, v110, v94, v94
	v_fma_f32 v111, v111, v95, v95
	v_mul_f32_e32 v104, 0x3fcc422a, v104
	v_mul_f32_e32 v105, 0x3fcc422a, v105
	v_mul_f32_e32 v106, 0x3fcc422a, v106
	v_mul_f32_e32 v107, 0x3fcc422a, v107
	v_mul_f32_e32 v108, 0x3fcc422a, v108
	v_mul_f32_e32 v109, 0x3fcc422a, v109
	v_mul_f32_e32 v110, 0x3fcc422a, v110
	v_mul_f32_e32 v111, 0x3fcc422a, v111
	v_mul_f32_e32 v104, 0xbfb8aa3b, v104
	v_mul_f32_e32 v105, 0xbfb8aa3b, v105
	v_mul_f32_e32 v106, 0xbfb8aa3b, v106
	v_mul_f32_e32 v107, 0xbfb8aa3b, v107
	v_mul_f32_e32 v108, 0xbfb8aa3b, v108
	v_mul_f32_e32 v109, 0xbfb8aa3b, v109
	v_mul_f32_e32 v110, 0xbfb8aa3b, v110
	v_mul_f32_e32 v111, 0xbfb8aa3b, v111
	v_exp_f32_e32 v104, v104
	v_exp_f32_e32 v105, v105
	v_exp_f32_e32 v106, v106
	v_exp_f32_e32 v107, v107
	v_exp_f32_e32 v108, v108
	v_exp_f32_e32 v109, v109
	v_exp_f32_e32 v110, v110
	v_exp_f32_e32 v111, v111
	v_add_f32_e32 v104, 1.0, v104
	v_add_f32_e32 v105, 1.0, v105
	v_add_f32_e32 v106, 1.0, v106
	v_add_f32_e32 v107, 1.0, v107
	v_add_f32_e32 v108, 1.0, v108
	v_add_f32_e32 v109, 1.0, v109
	v_add_f32_e32 v110, 1.0, v110
	v_add_f32_e32 v111, 1.0, v111
	v_rcp_f32_e32 v104, v104
	v_rcp_f32_e32 v105, v105
	v_rcp_f32_e32 v106, v106
	v_rcp_f32_e32 v107, v107
	v_rcp_f32_e32 v108, v108
	v_rcp_f32_e32 v109, v109
	v_rcp_f32_e32 v110, v110
	v_rcp_f32_e32 v111, v111
	v_mul_f32_e32 v104, v104, v88
	v_mul_f32_e32 v105, v105, v89
	v_mul_f32_e32 v106, v106, v90
	v_mul_f32_e32 v107, v107, v91
	v_mul_f32_e32 v108, v108, v92
	v_mul_f32_e32 v109, v109, v93
	v_mul_f32_e32 v110, v110, v94
	v_mul_f32_e32 v111, v111, v95
	v_mul_f32_e32 v104, v80, v104
	v_mul_f32_e32 v105, v81, v105
	v_mul_f32_e32 v106, v82, v106
	v_mul_f32_e32 v107, v83, v107
	v_mul_f32_e32 v108, v84, v108
	v_mul_f32_e32 v109, v85, v109
	v_mul_f32_e32 v110, v86, v110
	v_mul_f32_e32 v111, v87, v111
	v_cvt_pk_bf16_f32 v112, v104, v105
	v_cvt_pk_bf16_f32 v113, v106, v107
	v_cvt_pk_bf16_f32 v114, v108, v109
	v_cvt_pk_bf16_f32 v115, v110, v111
	global_store_dwordx4 v27, v[112:115], s[24:25]
	s_add_u32 s24, s24, 0x2800
	s_addc_u32 s25, s25, 0
	global_load_dwordx4 v[56:59], v26, s[12:13] nt
	global_load_dwordx4 v[60:63], v26, s[14:15] nt
	global_load_dwordx4 v[64:67], v26, s[96:97]
	s_add_u32 s12, s12, 0x800
	s_addc_u32 s13, s13, 0
	s_add_u32 s14, s14, 0x800
	s_addc_u32 s15, s15, 0
	s_add_u32 s96, s96, 0x2800
	s_addc_u32 s97, s97, 0
	s_waitcnt vmcnt(12)
	v_lshlrev_b32_e32 v80, 16, v68
	v_and_b32_e32 v81, 0xffff0000, v68
	v_lshlrev_b32_e32 v82, 16, v69
	v_and_b32_e32 v83, 0xffff0000, v69
	v_lshlrev_b32_e32 v84, 16, v70
	v_and_b32_e32 v85, 0xffff0000, v70
	v_lshlrev_b32_e32 v86, 16, v71
	v_and_b32_e32 v87, 0xffff0000, v71
	v_lshlrev_b32_e32 v96, 16, v72
	v_and_b32_e32 v97, 0xffff0000, v72
	v_lshlrev_b32_e32 v98, 16, v73
	v_and_b32_e32 v99, 0xffff0000, v73
	v_lshlrev_b32_e32 v100, 16, v74
	v_and_b32_e32 v101, 0xffff0000, v74
	v_lshlrev_b32_e32 v102, 16, v75
	v_and_b32_e32 v103, 0xffff0000, v75
	v_lshlrev_b32_e32 v88, 16, v76
	v_and_b32_e32 v89, 0xffff0000, v76
	v_lshlrev_b32_e32 v90, 16, v77
	v_and_b32_e32 v91, 0xffff0000, v77
	v_lshlrev_b32_e32 v92, 16, v78
	v_and_b32_e32 v93, 0xffff0000, v78
	v_lshlrev_b32_e32 v94, 16, v79
	v_and_b32_e32 v95, 0xffff0000, v79
	v_fmac_f32_e32 v80, v96, v18
	v_fmac_f32_e32 v81, v97, v19
	v_fmac_f32_e32 v82, v98, v20
	v_fmac_f32_e32 v83, v99, v21
	v_fmac_f32_e32 v84, v100, v22
	v_fmac_f32_e32 v85, v101, v23
	v_fmac_f32_e32 v86, v102, v24
	v_fmac_f32_e32 v87, v103, v25
	v_mul_f32_e32 v104, 0x3d372713, v88
	v_mul_f32_e32 v105, 0x3d372713, v89
	v_mul_f32_e32 v106, 0x3d372713, v90
	v_mul_f32_e32 v107, 0x3d372713, v91
	v_mul_f32_e32 v108, 0x3d372713, v92
	v_mul_f32_e32 v109, 0x3d372713, v93
	v_mul_f32_e32 v110, 0x3d372713, v94
	v_mul_f32_e32 v111, 0x3d372713, v95
	v_mul_f32_e32 v104, v104, v88
	v_mul_f32_e32 v105, v105, v89
	v_mul_f32_e32 v106, v106, v90
; __device__ __forceinline__ u32x4 pack8(const float (&f)[8]) { u32x4 o; o.x = cvt_pk_bf16(f[0], f[1]); o.y = cvt_pk_bf16(f[2], f[3]); o.z = cvt_pk_bf16(f[4], f[5]); o.w = cvt_pk_bf16(f[6], f[7]); return o; }
; __device__ __forceinline__ float gelu_tanh(float x) { return x * sigmoidf_(1.5957691216057308f * (x + 0.044715f * x * x * x)); }
; __device__ __forceinline__ void fixup_phase(KP p, int l) {
;     ...
;         for (int i = 0; i < 16; ++i) {
;             const size_t m = (size_t)(m0 + i);
;             float hl[8], pc[8], gr[8], o[8], h[8];
;             unpack8(__builtin_nontemporal_load((const u32x4*)(HLOC + m * D + c0)), hl); unpack8(__builtin_nontemporal_load((const u32x4*)(PCUM + m * D + c0)), pc);
;             bf16_t* gp = P + m * DP + C_GR + c0; unpack8(*(const u32x4*)gp, gr);
; #pragma unroll
;             for (int e = 0; e < 8; ++e) { h[e] = hl[e] + pc[e] * carry[e]; o[e] = gelu_tanh(gr[e]) * h[e]; }
;             *(u32x4*)gp = pack8(o);
	v_mul_f32_e32 v107, v107, v91
	v_mul_f32_e32 v108, v108, v92
	v_mul_f32_e32 v109, v109, v93
	v_mul_f32_e32 v110, v110, v94
	v_mul_f32_e32 v111, v111, v95
	v_fma_f32 v104, v104, v88, v88
	v_fma_f32 v105, v105, v89, v89
	v_fma_f32 v106, v106, v90, v90
	v_fma_f32 v107, v107, v91, v91
	v_fma_f32 v108, v108, v92, v92
	v_fma_f32 v109, v109, v93, v93
	v_fma_f32 v110, v110, v94, v94
	v_fma_f32 v111, v111, v95, v95
	v_mul_f32_e32 v104, 0x3fcc422a, v104
	v_mul_f32_e32 v105, 0x3fcc422a, v105
	v_mul_f32_e32 v106, 0x3fcc422a, v106
	v_mul_f32_e32 v107, 0x3fcc422a, v107
	v_mul_f32_e32 v108, 0x3fcc422a, v108
	v_mul_f32_e32 v109, 0x3fcc422a, v109
	v_mul_f32_e32 v110, 0x3fcc422a, v110
	v_mul_f32_e32 v111, 0x3fcc422a, v111
	v_mul_f32_e32 v104, 0xbfb8aa3b, v104
	v_mul_f32_e32 v105, 0xbfb8aa3b, v105
	v_mul_f32_e32 v106, 0xbfb8aa3b, v106
	v_mul_f32_e32 v107, 0xbfb8aa3b, v107
	v_mul_f32_e32 v108, 0xbfb8aa3b, v108
	v_mul_f32_e32 v109, 0xbfb8aa3b, v109
	v_mul_f32_e32 v110, 0xbfb8aa3b, v110
	v_mul_f32_e32 v111, 0xbfb8aa3b, v111
	v_exp_f32_e32 v104, v104
	v_exp_f32_e32 v105, v105
	v_exp_f32_e32 v106, v106
	v_exp_f32_e32 v107, v107
	v_exp_f32_e32 v108, v108
	v_exp_f32_e32 v109, v109
	v_exp_f32_e32 v110, v110
	v_exp_f32_e32 v111, v111
	v_add_f32_e32 v104, 1.0, v104
	v_add_f32_e32 v105, 1.0, v105
	v_add_f32_e32 v106, 1.0, v106
	v_add_f32_e32 v107, 1.0, v107
	v_add_f32_e32 v108, 1.0, v108
	v_add_f32_e32 v109, 1.0, v109
	v_add_f32_e32 v110, 1.0, v110
	v_add_f32_e32 v111, 1.0, v111
	v_rcp_f32_e32 v104, v104
	v_rcp_f32_e32 v105, v105
	v_rcp_f32_e32 v106, v106
	v_rcp_f32_e32 v107, v107
	v_rcp_f32_e32 v108, v108
	v_rcp_f32_e32 v109, v109
	v_rcp_f32_e32 v110, v110
	v_rcp_f32_e32 v111, v111
	v_mul_f32_e32 v104, v104, v88
	v_mul_f32_e32 v105, v105, v89
	v_mul_f32_e32 v106, v106, v90
	v_mul_f32_e32 v107, v107, v91
	v_mul_f32_e32 v108, v108, v92
	v_mul_f32_e32 v109, v109, v93
	v_mul_f32_e32 v110, v110, v94
	v_mul_f32_e32 v111, v111, v95
	v_mul_f32_e32 v104, v80, v104
	v_mul_f32_e32 v105, v81, v105
	v_mul_f32_e32 v106, v82, v106
	v_mul_f32_e32 v107, v83, v107
	v_mul_f32_e32 v108, v84, v108
	v_mul_f32_e32 v109, v85, v109
	v_mul_f32_e32 v110, v86, v110
	v_mul_f32_e32 v111, v87, v111
	v_cvt_pk_bf16_f32 v112, v104, v105
	v_cvt_pk_bf16_f32 v113, v106, v107
	v_cvt_pk_bf16_f32 v114, v108, v109
	v_cvt_pk_bf16_f32 v115, v110, v111
	global_store_dwordx4 v27, v[112:115], s[24:25]
	s_add_u32 s24, s24, 0x2800
	s_addc_u32 s25, s25, 0
	global_load_dwordx4 v[68:71], v26, s[12:13] nt
	global_load_dwordx4 v[72:75], v26, s[14:15] nt
	global_load_dwordx4 v[76:79], v26, s[96:97]
	s_add_u32 s12, s12, 0x800
	s_addc_u32 s13, s13, 0
	s_add_u32 s14, s14, 0x800
	s_addc_u32 s15, s15, 0
	s_add_u32 s96, s96, 0x2800
	s_addc_u32 s97, s97, 0
	s_waitcnt vmcnt(12)
	v_lshlrev_b32_e32 v80, 16, v32
	v_and_b32_e32 v81, 0xffff0000, v32
	v_lshlrev_b32_e32 v82, 16, v33
	v_and_b32_e32 v83, 0xffff0000, v33
	v_lshlrev_b32_e32 v84, 16, v34
	v_and_b32_e32 v85, 0xffff0000, v34
	v_lshlrev_b32_e32 v86, 16, v35
	v_and_b32_e32 v87, 0xffff0000, v35
	v_lshlrev_b32_e32 v96, 16, v36
	v_and_b32_e32 v97, 0xffff0000, v36
	v_lshlrev_b32_e32 v98, 16, v37
	v_and_b32_e32 v99, 0xffff0000, v37
	v_lshlrev_b32_e32 v100, 16, v38
	v_and_b32_e32 v101, 0xffff0000, v38
	v_lshlrev_b32_e32 v102, 16, v39
	v_and_b32_e32 v103, 0xffff0000, v39
	v_lshlrev_b32_e32 v88, 16, v40
	v_and_b32_e32 v89, 0xffff0000, v40
	v_lshlrev_b32_e32 v90, 16, v41
	v_and_b32_e32 v91, 0xffff0000, v41
	v_lshlrev_b32_e32 v92, 16, v42
	v_and_b32_e32 v93, 0xffff0000, v42
	v_lshlrev_b32_e32 v94, 16, v43
	v_and_b32_e32 v95, 0xffff0000, v43
	v_fmac_f32_e32 v80, v96, v18
	v_fmac_f32_e32 v81, v97, v19
	v_fmac_f32_e32 v82, v98, v20
	v_fmac_f32_e32 v83, v99, v21
	v_fmac_f32_e32 v84, v100, v22
	v_fmac_f32_e32 v85, v101, v23
	v_fmac_f32_e32 v86, v102, v24
	v_fmac_f32_e32 v87, v103, v25
	v_mul_f32_e32 v104, 0x3d372713, v88
	v_mul_f32_e32 v105, 0x3d372713, v89
	v_mul_f32_e32 v106, 0x3d372713, v90
	v_mul_f32_e32 v107, 0x3d372713, v91
	v_mul_f32_e32 v108, 0x3d372713, v92
	v_mul_f32_e32 v109, 0x3d372713, v93
	v_mul_f32_e32 v110, 0x3d372713, v94
	v_mul_f32_e32 v111, 0x3d372713, v95
	v_mul_f32_e32 v104, v104, v88
	v_mul_f32_e32 v105, v105, v89
	v_mul_f32_e32 v106, v106, v90
	v_mul_f32_e32 v107, v107, v91
	v_mul_f32_e32 v108, v108, v92
	v_mul_f32_e32 v109, v109, v93
	v_mul_f32_e32 v110, v110, v94
	v_mul_f32_e32 v111, v111, v95
	v_fma_f32 v104, v104, v88, v88
	v_fma_f32 v105, v105, v89, v89
	v_fma_f32 v106, v106, v90, v90
	v_fma_f32 v107, v107, v91, v91
	v_fma_f32 v108, v108, v92, v92
	v_fma_f32 v109, v109, v93, v93
	v_fma_f32 v110, v110, v94, v94
	v_fma_f32 v111, v111, v95, v95
	v_mul_f32_e32 v104, 0x3fcc422a, v104
	v_mul_f32_e32 v105, 0x3fcc422a, v105
	v_mul_f32_e32 v106, 0x3fcc422a, v106
	v_mul_f32_e32 v107, 0x3fcc422a, v107
	v_mul_f32_e32 v108, 0x3fcc422a, v108
	v_mul_f32_e32 v109, 0x3fcc422a, v109
	v_mul_f32_e32 v110, 0x3fcc422a, v110
	v_mul_f32_e32 v111, 0x3fcc422a, v111
	v_mul_f32_e32 v104, 0xbfb8aa3b, v104
	v_mul_f32_e32 v105, 0xbfb8aa3b, v105
	v_mul_f32_e32 v106, 0xbfb8aa3b, v106
	v_mul_f32_e32 v107, 0xbfb8aa3b, v107
	v_mul_f32_e32 v108, 0xbfb8aa3b, v108
	v_mul_f32_e32 v109, 0xbfb8aa3b, v109
	v_mul_f32_e32 v110, 0xbfb8aa3b, v110
	v_mul_f32_e32 v111, 0xbfb8aa3b, v111
	v_exp_f32_e32 v104, v104
	v_exp_f32_e32 v105, v105
	v_exp_f32_e32 v106, v106
	v_exp_f32_e32 v107, v107
	v_exp_f32_e32 v108, v108
	v_exp_f32_e32 v109, v109
	v_exp_f32_e32 v110, v110
	v_exp_f32_e32 v111, v111
	v_add_f32_e32 v104, 1.0, v104
	v_add_f32_e32 v105, 1.0, v105
	v_add_f32_e32 v106, 1.0, v106
	v_add_f32_e32 v107, 1.0, v107
	v_add_f32_e32 v108, 1.0, v108
	v_add_f32_e32 v109, 1.0, v109
	v_add_f32_e32 v110, 1.0, v110
	v_add_f32_e32 v111, 1.0, v111
	v_rcp_f32_e32 v104, v104
	v_rcp_f32_e32 v105, v105
	v_rcp_f32_e32 v106, v106
	v_rcp_f32_e32 v107, v107
	v_rcp_f32_e32 v108, v108
	v_rcp_f32_e32 v109, v109
	v_rcp_f32_e32 v110, v110
	v_rcp_f32_e32 v111, v111
	v_mul_f32_e32 v104, v104, v88
	v_mul_f32_e32 v105, v105, v89
	v_mul_f32_e32 v106, v106, v90
	v_mul_f32_e32 v107, v107, v91
	v_mul_f32_e32 v108, v108, v92
	v_mul_f32_e32 v109, v109, v93
	v_mul_f32_e32 v110, v110, v94
	v_mul_f32_e32 v111, v111, v95
	v_mul_f32_e32 v104, v80, v104
	v_mul_f32_e32 v105, v81, v105
	v_mul_f32_e32 v106, v82, v106
	v_mul_f32_e32 v107, v83, v107
	v_mul_f32_e32 v108, v84, v108
	v_mul_f32_e32 v109, v85, v109
	v_mul_f32_e32 v110, v86, v110
	v_mul_f32_e32 v111, v87, v111
	v_cvt_pk_bf16_f32 v112, v104, v105
	v_cvt_pk_bf16_f32 v113, v106, v107
	v_cvt_pk_bf16_f32 v114, v108, v109
	v_cvt_pk_bf16_f32 v115, v110, v111
	global_store_dwordx4 v27, v[112:115], s[24:25]
	s_add_u32 s24, s24, 0x2800
	s_addc_u32 s25, s25, 0
	s_waitcnt vmcnt(9)
; __device__ __forceinline__ u32x4 pack8(const float (&f)[8]) { u32x4 o; o.x = cvt_pk_bf16(f[0], f[1]); o.y = cvt_pk_bf16(f[2], f[3]); o.z = cvt_pk_bf16(f[4], f[5]); o.w = cvt_pk_bf16(f[6], f[7]); return o; }
; __device__ __forceinline__ float gelu_tanh(float x) { return x * sigmoidf_(1.5957691216057308f * (x + 0.044715f * x * x * x)); }
; __device__ __forceinline__ void fixup_phase(KP p, int l) {
;     ...
;         for (int i = 0; i < 16; ++i) {
;             const size_t m = (size_t)(m0 + i);
;             float hl[8], pc[8], gr[8], o[8], h[8];
;             unpack8(__builtin_nontemporal_load((const u32x4*)(HLOC + m * D + c0)), hl); unpack8(__builtin_nontemporal_load((const u32x4*)(PCUM + m * D + c0)), pc);
;             bf16_t* gp = P + m * DP + C_GR + c0; unpack8(*(const u32x4*)gp, gr);
; #pragma unroll
;             for (int e = 0; e < 8; ++e) { h[e] = hl[e] + pc[e] * carry[e]; o[e] = gelu_tanh(gr[e]) * h[e]; }
;             *(u32x4*)gp = pack8(o);
	v_lshlrev_b32_e32 v80, 16, v44
	v_and_b32_e32 v81, 0xffff0000, v44
	v_lshlrev_b32_e32 v82, 16, v45
	v_and_b32_e32 v83, 0xffff0000, v45
	v_lshlrev_b32_e32 v84, 16, v46
	v_and_b32_e32 v85, 0xffff0000, v46
	v_lshlrev_b32_e32 v86, 16, v47
	v_and_b32_e32 v87, 0xffff0000, v47
	v_lshlrev_b32_e32 v96, 16, v48
	v_and_b32_e32 v97, 0xffff0000, v48
	v_lshlrev_b32_e32 v98, 16, v49
	v_and_b32_e32 v99, 0xffff0000, v49
	v_lshlrev_b32_e32 v100, 16, v50
	v_and_b32_e32 v101, 0xffff0000, v50
	v_lshlrev_b32_e32 v102, 16, v51
	v_and_b32_e32 v103, 0xffff0000, v51
	v_lshlrev_b32_e32 v88, 16, v52
	v_and_b32_e32 v89, 0xffff0000, v52
	v_lshlrev_b32_e32 v90, 16, v53
	v_and_b32_e32 v91, 0xffff0000, v53
	v_lshlrev_b32_e32 v92, 16, v54
	v_and_b32_e32 v93, 0xffff0000, v54
	v_lshlrev_b32_e32 v94, 16, v55
	v_and_b32_e32 v95, 0xffff0000, v55
	v_fmac_f32_e32 v80, v96, v18
	v_fmac_f32_e32 v81, v97, v19
	v_fmac_f32_e32 v82, v98, v20
	v_fmac_f32_e32 v83, v99, v21
	v_fmac_f32_e32 v84, v100, v22
	v_fmac_f32_e32 v85, v101, v23
	v_fmac_f32_e32 v86, v102, v24
	v_fmac_f32_e32 v87, v103, v25
	v_mul_f32_e32 v104, 0x3d372713, v88
	v_mul_f32_e32 v105, 0x3d372713, v89
	v_mul_f32_e32 v106, 0x3d372713, v90
	v_mul_f32_e32 v107, 0x3d372713, v91
	v_mul_f32_e32 v108, 0x3d372713, v92
	v_mul_f32_e32 v109, 0x3d372713, v93
	v_mul_f32_e32 v110, 0x3d372713, v94
	v_mul_f32_e32 v111, 0x3d372713, v95
	v_mul_f32_e32 v104, v104, v88
	v_mul_f32_e32 v105, v105, v89
	v_mul_f32_e32 v106, v106, v90
	v_mul_f32_e32 v107, v107, v91
	v_mul_f32_e32 v108, v108, v92
	v_mul_f32_e32 v109, v109, v93
	v_mul_f32_e32 v110, v110, v94
	v_mul_f32_e32 v111, v111, v95
	v_fma_f32 v104, v104, v88, v88
	v_fma_f32 v105, v105, v89, v89
	v_fma_f32 v106, v106, v90, v90
	v_fma_f32 v107, v107, v91, v91
	v_fma_f32 v108, v108, v92, v92
	v_fma_f32 v109, v109, v93, v93
	v_fma_f32 v110, v110, v94, v94
	v_fma_f32 v111, v111, v95, v95
	v_mul_f32_e32 v104, 0x3fcc422a, v104
	v_mul_f32_e32 v105, 0x3fcc422a, v105
	v_mul_f32_e32 v106, 0x3fcc422a, v106
	v_mul_f32_e32 v107, 0x3fcc422a, v107
	v_mul_f32_e32 v108, 0x3fcc422a, v108
	v_mul_f32_e32 v109, 0x3fcc422a, v109
	v_mul_f32_e32 v110, 0x3fcc422a, v110
	v_mul_f32_e32 v111, 0x3fcc422a, v111
	v_mul_f32_e32 v104, 0xbfb8aa3b, v104
	v_mul_f32_e32 v105, 0xbfb8aa3b, v105
	v_mul_f32_e32 v106, 0xbfb8aa3b, v106
	v_mul_f32_e32 v107, 0xbfb8aa3b, v107
	v_mul_f32_e32 v108, 0xbfb8aa3b, v108
	v_mul_f32_e32 v109, 0xbfb8aa3b, v109
	v_mul_f32_e32 v110, 0xbfb8aa3b, v110
	v_mul_f32_e32 v111, 0xbfb8aa3b, v111
	v_exp_f32_e32 v104, v104
	v_exp_f32_e32 v105, v105
	v_exp_f32_e32 v106, v106
	v_exp_f32_e32 v107, v107
	v_exp_f32_e32 v108, v108
	v_exp_f32_e32 v109, v109
	v_exp_f32_e32 v110, v110
	v_exp_f32_e32 v111, v111
	v_add_f32_e32 v104, 1.0, v104
	v_add_f32_e32 v105, 1.0, v105
	v_add_f32_e32 v106, 1.0, v106
	v_add_f32_e32 v107, 1.0, v107
	v_add_f32_e32 v108, 1.0, v108
	v_add_f32_e32 v109, 1.0, v109
	v_add_f32_e32 v110, 1.0, v110
	v_add_f32_e32 v111, 1.0, v111
	v_rcp_f32_e32 v104, v104
	v_rcp_f32_e32 v105, v105
	v_rcp_f32_e32 v106, v106
	v_rcp_f32_e32 v107, v107
	v_rcp_f32_e32 v108, v108
	v_rcp_f32_e32 v109, v109
	v_rcp_f32_e32 v110, v110
	v_rcp_f32_e32 v111, v111
	v_mul_f32_e32 v104, v104, v88
	v_mul_f32_e32 v105, v105, v89
	v_mul_f32_e32 v106, v106, v90
	v_mul_f32_e32 v107, v107, v91
	v_mul_f32_e32 v108, v108, v92
	v_mul_f32_e32 v109, v109, v93
	v_mul_f32_e32 v110, v110, v94
	v_mul_f32_e32 v111, v111, v95
	v_mul_f32_e32 v104, v80, v104
	v_mul_f32_e32 v105, v81, v105
	v_mul_f32_e32 v106, v82, v106
	v_mul_f32_e32 v107, v83, v107
	v_mul_f32_e32 v108, v84, v108
	v_mul_f32_e32 v109, v85, v109
	v_mul_f32_e32 v110, v86, v110
	v_mul_f32_e32 v111, v87, v111
	v_cvt_pk_bf16_f32 v112, v104, v105
	v_cvt_pk_bf16_f32 v113, v106, v107
	v_cvt_pk_bf16_f32 v114, v108, v109
	v_cvt_pk_bf16_f32 v115, v110, v111
	global_store_dwordx4 v27, v[112:115], s[24:25]
	s_add_u32 s24, s24, 0x2800
	s_addc_u32 s25, s25, 0
	s_waitcnt vmcnt(6)
	v_lshlrev_b32_e32 v80, 16, v56
	v_and_b32_e32 v81, 0xffff0000, v56
	v_lshlrev_b32_e32 v82, 16, v57
	v_and_b32_e32 v83, 0xffff0000, v57
	v_lshlrev_b32_e32 v84, 16, v58
	v_and_b32_e32 v85, 0xffff0000, v58
	v_lshlrev_b32_e32 v86, 16, v59
	v_and_b32_e32 v87, 0xffff0000, v59
	v_lshlrev_b32_e32 v96, 16, v60
	v_and_b32_e32 v97, 0xffff0000, v60
	v_lshlrev_b32_e32 v98, 16, v61
	v_and_b32_e32 v99, 0xffff0000, v61
	v_lshlrev_b32_e32 v100, 16, v62
	v_and_b32_e32 v101, 0xffff0000, v62
	v_lshlrev_b32_e32 v102, 16, v63
	v_and_b32_e32 v103, 0xffff0000, v63
	v_lshlrev_b32_e32 v88, 16, v64
	v_and_b32_e32 v89, 0xffff0000, v64
	v_lshlrev_b32_e32 v90, 16, v65
	v_and_b32_e32 v91, 0xffff0000, v65
	v_lshlrev_b32_e32 v92, 16, v66
	v_and_b32_e32 v93, 0xffff0000, v66
	v_lshlrev_b32_e32 v94, 16, v67
	v_and_b32_e32 v95, 0xffff0000, v67
	v_fmac_f32_e32 v80, v96, v18
	v_fmac_f32_e32 v81, v97, v19
	v_fmac_f32_e32 v82, v98, v20
	v_fmac_f32_e32 v83, v99, v21
	v_fmac_f32_e32 v84, v100, v22
	v_fmac_f32_e32 v85, v101, v23
	v_fmac_f32_e32 v86, v102, v24
	v_fmac_f32_e32 v87, v103, v25
	v_mul_f32_e32 v104, 0x3d372713, v88
	v_mul_f32_e32 v105, 0x3d372713, v89
	v_mul_f32_e32 v106, 0x3d372713, v90
	v_mul_f32_e32 v107, 0x3d372713, v91
	v_mul_f32_e32 v108, 0x3d372713, v92
	v_mul_f32_e32 v109, 0x3d372713, v93
	v_mul_f32_e32 v110, 0x3d372713, v94
	v_mul_f32_e32 v111, 0x3d372713, v95
	v_mul_f32_e32 v104, v104, v88
	v_mul_f32_e32 v105, v105, v89
	v_mul_f32_e32 v106, v106, v90
	v_mul_f32_e32 v107, v107, v91
	v_mul_f32_e32 v108, v108, v92
	v_mul_f32_e32 v109, v109, v93
	v_mul_f32_e32 v110, v110, v94
	v_mul_f32_e32 v111, v111, v95
	v_fma_f32 v104, v104, v88, v88
	v_fma_f32 v105, v105, v89, v89
	v_fma_f32 v106, v106, v90, v90
	v_fma_f32 v107, v107, v91, v91
; __device__ __forceinline__ u32x4 pack8(const float (&f)[8]) { u32x4 o; o.x = cvt_pk_bf16(f[0], f[1]); o.y = cvt_pk_bf16(f[2], f[3]); o.z = cvt_pk_bf16(f[4], f[5]); o.w = cvt_pk_bf16(f[6], f[7]); return o; }
; __device__ __forceinline__ float gelu_tanh(float x) { return x * sigmoidf_(1.5957691216057308f * (x + 0.044715f * x * x * x)); }
; __device__ __forceinline__ void fixup_phase(KP p, int l) {
;     ...
;         for (int i = 0; i < 16; ++i) {
;             const size_t m = (size_t)(m0 + i);
;             float hl[8], pc[8], gr[8], o[8], h[8];
;             unpack8(__builtin_nontemporal_load((const u32x4*)(HLOC + m * D + c0)), hl); unpack8(__builtin_nontemporal_load((const u32x4*)(PCUM + m * D + c0)), pc);
;             bf16_t* gp = P + m * DP + C_GR + c0; unpack8(*(const u32x4*)gp, gr);
; #pragma unroll
;             for (int e = 0; e < 8; ++e) { h[e] = hl[e] + pc[e] * carry[e]; o[e] = gelu_tanh(gr[e]) * h[e]; }
;             *(u32x4*)gp = pack8(o);
;             if (tile < 1032 && t0 + i == TP - 1) store8f(p->out + O_PRG + (size_t)(l * NB + b) * D + c0, h);
	v_fma_f32 v108, v108, v92, v92
	v_fma_f32 v109, v109, v93, v93
	v_fma_f32 v110, v110, v94, v94
	v_fma_f32 v111, v111, v95, v95
	v_mul_f32_e32 v104, 0x3fcc422a, v104
	v_mul_f32_e32 v105, 0x3fcc422a, v105
	v_mul_f32_e32 v106, 0x3fcc422a, v106
	v_mul_f32_e32 v107, 0x3fcc422a, v107
	v_mul_f32_e32 v108, 0x3fcc422a, v108
	v_mul_f32_e32 v109, 0x3fcc422a, v109
	v_mul_f32_e32 v110, 0x3fcc422a, v110
	v_mul_f32_e32 v111, 0x3fcc422a, v111
	v_mul_f32_e32 v104, 0xbfb8aa3b, v104
	v_mul_f32_e32 v105, 0xbfb8aa3b, v105
	v_mul_f32_e32 v106, 0xbfb8aa3b, v106
	v_mul_f32_e32 v107, 0xbfb8aa3b, v107
	v_mul_f32_e32 v108, 0xbfb8aa3b, v108
	v_mul_f32_e32 v109, 0xbfb8aa3b, v109
	v_mul_f32_e32 v110, 0xbfb8aa3b, v110
	v_mul_f32_e32 v111, 0xbfb8aa3b, v111
	v_exp_f32_e32 v104, v104
	v_exp_f32_e32 v105, v105
	v_exp_f32_e32 v106, v106
	v_exp_f32_e32 v107, v107
	v_exp_f32_e32 v108, v108
	v_exp_f32_e32 v109, v109
	v_exp_f32_e32 v110, v110
	v_exp_f32_e32 v111, v111
	v_add_f32_e32 v104, 1.0, v104
	v_add_f32_e32 v105, 1.0, v105
	v_add_f32_e32 v106, 1.0, v106
	v_add_f32_e32 v107, 1.0, v107
	v_add_f32_e32 v108, 1.0, v108
	v_add_f32_e32 v109, 1.0, v109
	v_add_f32_e32 v110, 1.0, v110
	v_add_f32_e32 v111, 1.0, v111
	v_rcp_f32_e32 v104, v104
	v_rcp_f32_e32 v105, v105
	v_rcp_f32_e32 v106, v106
	v_rcp_f32_e32 v107, v107
	v_rcp_f32_e32 v108, v108
	v_rcp_f32_e32 v109, v109
	v_rcp_f32_e32 v110, v110
	v_rcp_f32_e32 v111, v111
	v_mul_f32_e32 v104, v104, v88
	v_mul_f32_e32 v105, v105, v89
	v_mul_f32_e32 v106, v106, v90
	v_mul_f32_e32 v107, v107, v91
	v_mul_f32_e32 v108, v108, v92
	v_mul_f32_e32 v109, v109, v93
	v_mul_f32_e32 v110, v110, v94
	v_mul_f32_e32 v111, v111, v95
	v_mul_f32_e32 v104, v80, v104
	v_mul_f32_e32 v105, v81, v105
	v_mul_f32_e32 v106, v82, v106
	v_mul_f32_e32 v107, v83, v107
	v_mul_f32_e32 v108, v84, v108
	v_mul_f32_e32 v109, v85, v109
	v_mul_f32_e32 v110, v86, v110
	v_mul_f32_e32 v111, v87, v111
	v_cvt_pk_bf16_f32 v112, v104, v105
	v_cvt_pk_bf16_f32 v113, v106, v107
	v_cvt_pk_bf16_f32 v114, v108, v109
	v_cvt_pk_bf16_f32 v115, v110, v111
	global_store_dwordx4 v27, v[112:115], s[24:25]
	s_add_u32 s24, s24, 0x2800
	s_addc_u32 s25, s25, 0
	s_waitcnt vmcnt(3)
	v_lshlrev_b32_e32 v80, 16, v68
	v_and_b32_e32 v81, 0xffff0000, v68
	v_lshlrev_b32_e32 v82, 16, v69
	v_and_b32_e32 v83, 0xffff0000, v69
	v_lshlrev_b32_e32 v84, 16, v70
	v_and_b32_e32 v85, 0xffff0000, v70
	v_lshlrev_b32_e32 v86, 16, v71
	v_and_b32_e32 v87, 0xffff0000, v71
	v_lshlrev_b32_e32 v96, 16, v72
	v_and_b32_e32 v97, 0xffff0000, v72
	v_lshlrev_b32_e32 v98, 16, v73
	v_and_b32_e32 v99, 0xffff0000, v73
	v_lshlrev_b32_e32 v100, 16, v74
	v_and_b32_e32 v101, 0xffff0000, v74
	v_lshlrev_b32_e32 v102, 16, v75
	v_and_b32_e32 v103, 0xffff0000, v75
	v_lshlrev_b32_e32 v88, 16, v76
	v_and_b32_e32 v89, 0xffff0000, v76
	v_lshlrev_b32_e32 v90, 16, v77
	v_and_b32_e32 v91, 0xffff0000, v77
	v_lshlrev_b32_e32 v92, 16, v78
	v_and_b32_e32 v93, 0xffff0000, v78
	v_lshlrev_b32_e32 v94, 16, v79
	v_and_b32_e32 v95, 0xffff0000, v79
	v_fmac_f32_e32 v80, v96, v18
	v_fmac_f32_e32 v81, v97, v19
	v_fmac_f32_e32 v82, v98, v20
	v_fmac_f32_e32 v83, v99, v21
	v_fmac_f32_e32 v84, v100, v22
	v_fmac_f32_e32 v85, v101, v23
	v_fmac_f32_e32 v86, v102, v24
	v_fmac_f32_e32 v87, v103, v25
	v_mul_f32_e32 v104, 0x3d372713, v88
	v_mul_f32_e32 v105, 0x3d372713, v89
	v_mul_f32_e32 v106, 0x3d372713, v90
	v_mul_f32_e32 v107, 0x3d372713, v91
	v_mul_f32_e32 v108, 0x3d372713, v92
	v_mul_f32_e32 v109, 0x3d372713, v93
	v_mul_f32_e32 v110, 0x3d372713, v94
	v_mul_f32_e32 v111, 0x3d372713, v95
	v_mul_f32_e32 v104, v104, v88
	v_mul_f32_e32 v105, v105, v89
	v_mul_f32_e32 v106, v106, v90
	v_mul_f32_e32 v107, v107, v91
	v_mul_f32_e32 v108, v108, v92
	v_mul_f32_e32 v109, v109, v93
	v_mul_f32_e32 v110, v110, v94
	v_mul_f32_e32 v111, v111, v95
	v_fma_f32 v104, v104, v88, v88
	v_fma_f32 v105, v105, v89, v89
	v_fma_f32 v106, v106, v90, v90
	v_fma_f32 v107, v107, v91, v91
	v_fma_f32 v108, v108, v92, v92
	v_fma_f32 v109, v109, v93, v93
	v_fma_f32 v110, v110, v94, v94
	v_fma_f32 v111, v111, v95, v95
	v_mul_f32_e32 v104, 0x3fcc422a, v104
	v_mul_f32_e32 v105, 0x3fcc422a, v105
	v_mul_f32_e32 v106, 0x3fcc422a, v106
	v_mul_f32_e32 v107, 0x3fcc422a, v107
	v_mul_f32_e32 v108, 0x3fcc422a, v108
	v_mul_f32_e32 v109, 0x3fcc422a, v109
	v_mul_f32_e32 v110, 0x3fcc422a, v110
	v_mul_f32_e32 v111, 0x3fcc422a, v111
	v_mul_f32_e32 v104, 0xbfb8aa3b, v104
	v_mul_f32_e32 v105, 0xbfb8aa3b, v105
	v_mul_f32_e32 v106, 0xbfb8aa3b, v106
	v_mul_f32_e32 v107, 0xbfb8aa3b, v107
	v_mul_f32_e32 v108, 0xbfb8aa3b, v108
	v_mul_f32_e32 v109, 0xbfb8aa3b, v109
	v_mul_f32_e32 v110, 0xbfb8aa3b, v110
	v_mul_f32_e32 v111, 0xbfb8aa3b, v111
	v_exp_f32_e32 v104, v104
	v_exp_f32_e32 v105, v105
	v_exp_f32_e32 v106, v106
	v_exp_f32_e32 v107, v107
	v_exp_f32_e32 v108, v108
	v_exp_f32_e32 v109, v109
	v_exp_f32_e32 v110, v110
	v_exp_f32_e32 v111, v111
	v_add_f32_e32 v104, 1.0, v104
	v_add_f32_e32 v105, 1.0, v105
	v_add_f32_e32 v106, 1.0, v106
	v_add_f32_e32 v107, 1.0, v107
	v_add_f32_e32 v108, 1.0, v108
	v_add_f32_e32 v109, 1.0, v109
	v_add_f32_e32 v110, 1.0, v110
	v_add_f32_e32 v111, 1.0, v111
	v_rcp_f32_e32 v104, v104
	v_rcp_f32_e32 v105, v105
	v_rcp_f32_e32 v106, v106
	v_rcp_f32_e32 v107, v107
	v_rcp_f32_e32 v108, v108
	v_rcp_f32_e32 v109, v109
	v_rcp_f32_e32 v110, v110
	v_rcp_f32_e32 v111, v111
	v_mul_f32_e32 v104, v104, v88
	v_mul_f32_e32 v105, v105, v89
	v_mul_f32_e32 v106, v106, v90
	v_mul_f32_e32 v107, v107, v91
	v_mul_f32_e32 v108, v108, v92
	v_mul_f32_e32 v109, v109, v93
	v_mul_f32_e32 v110, v110, v94
	v_mul_f32_e32 v111, v111, v95
	v_mul_f32_e32 v104, v80, v104
	v_mul_f32_e32 v105, v81, v105
	v_mul_f32_e32 v106, v82, v106
	v_mul_f32_e32 v107, v83, v107
	v_mul_f32_e32 v108, v84, v108
	v_mul_f32_e32 v109, v85, v109
	v_mul_f32_e32 v110, v86, v110
	v_mul_f32_e32 v111, v87, v111
	v_cvt_pk_bf16_f32 v112, v104, v105
	v_cvt_pk_bf16_f32 v113, v106, v107
	v_cvt_pk_bf16_f32 v114, v108, v109
	v_cvt_pk_bf16_f32 v115, v110, v111
	global_store_dwordx4 v27, v[112:115], s[24:25]
	s_cmp_eq_u32 s43, 0
	s_cbranch_scc1 .Lfx_noprg
	s_lshl_b32 s44, s18, 12
	s_lshl_b32 s23, s10, 12
	s_add_i32 s44, s44, s23
	s_add_u32 s98, s72, 0x4120000
	s_addc_u32 s99, s73, 0
	s_add_u32 s98, s98, s44
	s_addc_u32 s99, s99, 0
	global_store_dwordx4 v31, v[80:83], s[98:99]
	global_store_dwordx4 v31, v[84:87], s[98:99] offset:16
; #define LAS __attribute__((address_space(3)))
; __device__ __forceinline__ KP kargs() { KP k = (KP)__builtin_amdgcn_kernarg_segment_ptr(); asm volatile("" : "+s"(k)); return k; }
; __device__ __forceinline__ int tid_() { int t = threadIdx.x; asm volatile("" : "+v"(t)); return t; }
; __device__ __forceinline__ unsigned xb_ld(unsigned* p)              { return __hip_atomic_load(p, __ATOMIC_RELAXED, __HIP_MEMORY_SCOPE_AGENT); }
; __device__ __forceinline__ unsigned xb_add(unsigned* p, unsigned v) { return __hip_atomic_fetch_add(p, v, __ATOMIC_RELAXED, __HIP_MEMORY_SCOPE_AGENT); }
; __device__ __forceinline__ unsigned xb_xcc_id() { return (unsigned)__builtin_amdgcn_s_getreg((3 << 11) | 20) & 0xFu; }
; #define XB_SPIN(cond, bar) do { unsigned _sp = 0; while (cond) { __builtin_amdgcn_s_sleep(1); \
;     if ((++_sp & 255u) == 0u) { if (xb_ld(&(bar)[XB_TMO])) break; if (_sp > XB_SPIN_CAP) { atomicAdd(&(bar)[XB_TMO], 1u); break; } } } } while (0)
; __device__ __forceinline__ void fixup_phase(KP p, int l) {
;     ...
;     for (int it = gt; it < (M / 16) * 128; it += NT) {
; __device__ __forceinline__ void grid_barrier(LAS unsigned char* lds) {
;     ...
;     if (tid_() == 0) {
;         unsigned* bar = (unsigned*)(kargs()->ws + WS_BAR);
;         volatile LAS unsigned* st = (volatile LAS unsigned*)(lds + LDS_BAR_OFF);
;         const unsigned x = xb_xcc_id();
;         __builtin_amdgcn_s_waitcnt(0);
;         unsigned nloc = st[0], nx = st[1];
;         if (nloc == 0u) { xcd_barrier_complete(bar, x, nloc, nx); st[0] = nloc; st[1] = nx; }
;         const unsigned old = xb_add(&bar[XB_XSUB(x)], 1u);
;         const unsigned gen = old / nloc;
;         if (old + 1u == (gen + 1u) * nloc) {
;             __builtin_amdgcn_fence(__ATOMIC_RELEASE, "agent");
;             asm volatile("s_waitcnt vmcnt(0)" ::: "memory");
;             const unsigned og = xb_add(&bar[XB_TOP], 1u);
;             const unsigned tg = og / nx;
;             if (og + 1u == (tg + 1u) * nx) xb_add(&bar[XB_TOPGEN], 1u);
;             else XB_SPIN(xb_ld(&bar[XB_TOPGEN]) == tg, bar);
;             __builtin_amdgcn_fence(__ATOMIC_ACQUIRE, "agent");
;             xb_add(&bar[XB_XGEN(x)], 1u);
.Lfx_noprg:
	s_add_u32 s24, s24, 0x2800
	s_addc_u32 s25, s25, 0
	s_add_i32 s57, s57, s16
	s_branch .Lfx_loop
.Lfx_done:
.LBB0_426:
	s_or_b64 exec, exec, s[8:9]
	s_waitcnt vmcnt(0)
	v_mov_b32_e32 v0, v209
	s_barrier
	s_nop 0
	v_cmp_eq_u32_e32 vcc, 0, v0
	s_and_saveexec_b64 s[4:5], vcc
	s_cbranch_execz .LBB0_478
	v_readlane_b32 s12, v255, 8
	v_readlane_b32 s13, v255, 9
	v_mov_b32_e32 v18, 0x20000
	ds_read2_b32 v[20:21], v18 offset1:1
	s_getreg_b32 s14, hwreg(HW_REG_XCC_ID, 0, 4)
	s_and_b32 s14, s14, 15
	s_mul_i32 s32, s56, 8
	s_add_i32 s32, s32, 3
	s_add_i32 s34, s32, 1
	v_mov_b32_e32 v19, 1
	v_mov_b32_e32 v22, 0
	s_waitcnt lgkmcnt(0)
	v_readfirstlane_b32 s24, v20
	v_readfirstlane_b32 s25, v21
	s_lshl_b32 s35, s14, 8
	s_add_u32 s70, s12, s35
	s_addc_u32 s71, s13, 0
	s_add_u32 s72, s70, 0x2400
	s_addc_u32 s73, s71, 0
	s_add_u32 s70, s70, 0x1400
	s_addc_u32 s71, s71, 0
	global_atomic_add v23, v22, v19, s[70:71] sc0
	s_mul_i32 s57, s34, s24
	s_waitcnt vmcnt(0)
	v_readfirstlane_b32 s44, v23
	s_nop 3
	s_add_i32 s44, s44, 1
	s_cmp_lg_u32 s44, s57
	s_cbranch_scc1 .Lfb4_spin
	buffer_wbl2 sc1
	s_waitcnt vmcnt(0)
	s_add_u32 s98, s12, 0x3400
	s_addc_u32 s99, s13, 0
	global_atomic_add v23, v22, v19, s[98:99] sc0
	s_mul_i32 s57, s34, s25
	s_waitcnt vmcnt(0)
	v_readfirstlane_b32 s44, v23
	s_nop 3
	s_add_i32 s44, s44, 1
	s_cmp_lg_u32 s44, s57
	s_cbranch_scc1 .Lfb4_spin
	global_atomic_add v22, v19, s[98:99] offset:256
	s_add_u32 s98, s12, 0x2400
	s_addc_u32 s99, s13, 0
	global_atomic_add v22, v19, s[98:99]
	global_atomic_add v22, v19, s[98:99] offset:256
	global_atomic_add v22, v19, s[98:99] offset:512
	global_atomic_add v22, v19, s[98:99] offset:768
	global_atomic_add v22, v19, s[98:99] offset:1024
	global_atomic_add v22, v19, s[98:99] offset:1280
	global_atomic_add v22, v19, s[98:99] offset:1536
	global_atomic_add v22, v19, s[98:99] offset:1792
	global_atomic_add v22, v19, s[98:99] offset:2048
	global_atomic_add v22, v19, s[98:99] offset:2304
	global_atomic_add v22, v19, s[98:99] offset:2560
	global_atomic_add v22, v19, s[98:99] offset:2816
	global_atomic_add v22, v19, s[98:99] offset:3072
	global_atomic_add v22, v19, s[98:99] offset:3328
	global_atomic_add v22, v19, s[98:99] offset:3584
	global_atomic_add v22, v19, s[98:99] offset:3840
